# plus: LRU-gates epilogue xb loads hoisted
# baseline (speedup 1.0000x reference)
; #define PG8_STAGE(bufoff, gbase, voff) do { _Pragma("unroll") for (int _i = 0; _i < 2; ++_i) \
;         __builtin_amdgcn_global_load_lds((const unsigned*)((const char*)(gbase) + (voff)[_i]), (LAS unsigned*)(lds + (bufoff) + ldsw + _i * 8192), 16, 0, 0); } while (0)
; #define PG8_LDA(dst, b, h) do { _Pragma("unroll") for (int m = 0; m < 4; ++m) _Pragma("unroll") for (int k = 0; k < 2; ++k) dst[m][k] = *(const LAS bf16x8*)(lds + PG8_SA(b, h) + aoff + m * 2048 + k * 1024); } while (0)
; #define PG8_LDB(dst, b, h) do { _Pragma("unroll") for (int n = 0; n < 2; ++n) _Pragma("unroll") for (int k = 0; k < 2; ++k) dst[n][k] = *(const LAS bf16x8*)(lds + PG8_SB(b, h) + boff + n * 2048 + k * 1024); } while (0)
; #define PG8_MMA(ai, bj, At, Bt) do { __builtin_amdgcn_s_setprio(1); _Pragma("unroll") for (int m = 0; m < 4; ++m) _Pragma("unroll") for (int n = 0; n < 2; ++n) _Pragma("unroll") for (int k = 0; k < 2; ++k) \
;         acc[ai][bj][m][n] = __builtin_amdgcn_mfma_f32_16x16x32_bf16(Bt[n][k], At[m][k], acc[ai][bj][m][n], 0, 0, 0); __builtin_amdgcn_s_setprio(0); } while (0)
; #define PG8_WAIT_L(n) asm volatile("s_waitcnt lgkmcnt(" #n ")" ::: "memory")
; #define PG8_BAR __builtin_amdgcn_s_barrier()
; #define PG8_SCHED __builtin_amdgcn_sched_barrier(0)
; template <class Epi, int KK, int LDA, int LDB, int NN, bool AGRP>
; __device__ __forceinline__ void gemm_phase(LAS unsigned char* lds, const bf16_t* gA, const bf16_t* gBt, int G_, int bid_, int tid) {
;     ...
;             const char* a1 = cA + (size_t)(t + 1) * kstep;
;             const char* a2 = last ? nA : cA + (size_t)(t + 2) * kstep; const char* b2 = last ? nB : cB + (size_t)(t + 2) * kstep;
;             const char* a3 = a2 + kstep; const char* b3 = b2 + kstep;
;             PG8_LDB(B0, 0, 0); PG8_SCHED; PG8_LDA(At, 0, 0); PG8_STAGE(PG8_SA(1, 1), a1 + hstepA, voffA);
;             PG8_WAIT_L(8); PG8_BAR; PG8_WAIT_L(0); PG8_MMA(0, 0, At, B0); PG8_BAR; PG8_SCHED;
;             PG8_LDB(B1, 0, 1); PG8_STAGE(PG8_SB(0, 0), b2, voffB);
;             PG8_BAR; PG8_WAIT_L(0); PG8_MMA(0, 1, At, B1); PG8_BAR;
;             PG8_LDA(At, 0, 1); PG8_STAGE(PG8_SA(0, 0), a2, voffA);
;             PG8_BAR; PG8_WAIT_L(0); PG8_MMA(1, 0, At, B0); PG8_BAR; PG8_SCHED;
.LBB1_281:
	s_add_u32 s36, s18, s24
	s_addc_u32 s37, s19, s25
	s_add_u32 s28, s36, 0x100
	s_addc_u32 s29, s37, 0
	s_and_b64 s[26:27], s[22:23], exec
	s_cselect_b32 s29, s1, s29
	s_cselect_b32 s28, s7, s28
	s_add_u32 s24, s16, s24
	s_addc_u32 s25, s17, s25
	s_add_u32 s24, s24, 0x100
	s_addc_u32 s25, s25, 0
	s_and_b64 s[22:23], s[22:23], exec
	s_cselect_b32 s31, s9, s25
	s_cselect_b32 s30, s35, s24
	s_add_u32 s36, s36, 0x40080
	v_add_u32_e32 v78, s44, v166
	s_addc_u32 s37, s37, 0
	s_add_i32 m0, s47, 0xc000
	s_add_i32 s65, s47, 0xe000
	ds_read_b128 v[66:69], v78
	ds_read_b128 v[70:73], v78 offset:1024
	ds_read_b128 v[74:77], v78 offset:2048
	ds_read_b128 v[78:81], v78 offset:3072
	s_add_u32 s26, s30, 0x10000
	s_addc_u32 s27, s31, 0
	s_add_u32 s24, s28, 0x40000
	s_addc_u32 s25, s29, 0
	s_add_u32 s22, s30, 0x10080
	s_addc_u32 s23, s31, 0
	v_lshl_add_u64 v[200:201], s[36:37], 0, v[158:159]
	ds_read_b128 v[82:85], v168
	ds_read_b128 v[86:89], v168 offset:1024
	ds_read_b128 v[160:163], v168 offset:2048
	ds_read_b128 v[176:179], v168 offset:3072
	ds_read_b128 v[180:183], v168 offset:4096
	ds_read_b128 v[184:187], v168 offset:5120
	ds_read_b128 v[188:191], v168 offset:6144
	ds_read_b128 v[194:197], v168 offset:7168
	global_load_lds_dwordx4 v[200:201], off
	v_lshl_add_u64 v[200:201], s[36:37], 0, v[156:157]
	s_mov_b32 m0, s65
	s_nop 0
	global_load_lds_dwordx4 v[200:201], off
	s_waitcnt lgkmcnt(8)
	s_barrier
	s_waitcnt lgkmcnt(0)
	s_setprio 1
	s_waitcnt lgkmcnt(0)
	v_mfma_f32_16x16x32_bf16 v[150:153], v[66:69], v[82:85], v[150:153]
	v_mfma_f32_16x16x32_bf16 v[142:145], v[74:77], v[82:85], v[142:145]
	v_mfma_f32_16x16x32_bf16 v[134:137], v[66:69], v[160:163], v[134:137]
	v_mfma_f32_16x16x32_bf16 v[126:129], v[74:77], v[160:163], v[126:129]
	v_mfma_f32_16x16x32_bf16 v[118:121], v[66:69], v[180:183], v[118:121]
	v_mfma_f32_16x16x32_bf16 v[110:113], v[74:77], v[180:183], v[110:113]
	v_mfma_f32_16x16x32_bf16 v[102:105], v[66:69], v[188:191], v[102:105]
	v_mfma_f32_16x16x32_bf16 v[94:97], v[74:77], v[188:191], v[94:97]
	v_mfma_f32_16x16x32_bf16 v[150:153], v[70:73], v[86:89], v[150:153]
	v_mfma_f32_16x16x32_bf16 v[142:145], v[78:81], v[86:89], v[142:145]
	v_mfma_f32_16x16x32_bf16 v[134:137], v[70:73], v[176:179], v[134:137]
	v_mfma_f32_16x16x32_bf16 v[126:129], v[78:81], v[176:179], v[126:129]
	v_mfma_f32_16x16x32_bf16 v[118:121], v[70:73], v[184:187], v[118:121]
	v_mfma_f32_16x16x32_bf16 v[110:113], v[78:81], v[184:187], v[110:113]
	v_mfma_f32_16x16x32_bf16 v[102:105], v[70:73], v[194:197], v[102:105]
	v_mfma_f32_16x16x32_bf16 v[94:97], v[78:81], v[194:197], v[94:97]
	s_setprio 0
	s_barrier
	s_mov_b32 m0, s45
	v_add_u32_e32 v169, s49, v166
	v_lshl_add_u64 v[216:217], s[30:31], 0, v[4:5]
	ds_read_b128 v[200:203], v169
	ds_read_b128 v[204:207], v169 offset:1024
	ds_read_b128 v[208:211], v169 offset:2048
	ds_read_b128 v[212:215], v169 offset:3072
	global_load_lds_dwordx4 v[216:217], off
	v_lshl_add_u64 v[218:219], s[30:31], 0, v[154:155]
	s_mov_b32 m0, s46
	s_nop 0
	global_load_lds_dwordx4 v[218:219], off
	s_barrier
	s_waitcnt lgkmcnt(0)
	s_setprio 1
	s_waitcnt lgkmcnt(0)
	v_mfma_f32_16x16x32_bf16 v[146:149], v[200:203], v[82:85], v[146:149]
	v_mfma_f32_16x16x32_bf16 v[82:85], v[208:211], v[82:85], v[138:141]
	v_mfma_f32_16x16x32_bf16 v[122:125], v[208:211], v[160:163], v[122:125]
	v_mfma_f32_16x16x32_bf16 v[114:117], v[200:203], v[180:183], v[114:117]
	v_mfma_f32_16x16x32_bf16 v[106:109], v[208:211], v[180:183], v[106:109]
	v_mfma_f32_16x16x32_bf16 v[98:101], v[200:203], v[188:191], v[98:101]
	v_mfma_f32_16x16x32_bf16 v[90:93], v[208:211], v[188:191], v[90:93]
	v_mfma_f32_16x16x32_bf16 v[146:149], v[204:207], v[86:89], v[146:149]
	v_mfma_f32_16x16x32_bf16 v[82:85], v[212:215], v[86:89], v[82:85]
	v_mfma_f32_16x16x32_bf16 v[86:89], v[200:203], v[160:163], v[130:133]
	v_mfma_f32_16x16x32_bf16 v[122:125], v[212:215], v[176:179], v[122:125]
	v_mfma_f32_16x16x32_bf16 v[114:117], v[204:207], v[184:187], v[114:117]
	v_mfma_f32_16x16x32_bf16 v[106:109], v[212:215], v[184:187], v[106:109]
	v_mfma_f32_16x16x32_bf16 v[98:101], v[204:207], v[194:197], v[98:101]
	v_mfma_f32_16x16x32_bf16 v[90:93], v[212:215], v[194:197], v[90:93]
	v_mfma_f32_16x16x32_bf16 v[86:89], v[204:207], v[176:179], v[86:89]
	s_setprio 0
	s_mov_b32 m0, s47
	v_lshl_add_u64 v[220:221], s[28:29], 0, v[158:159]
	s_barrier
	ds_read_b128 v[130:133], v168 offset:16384
	ds_read_b128 v[138:141], v168 offset:17408
	ds_read_b128 v[160:163], v168 offset:18432
	ds_read_b128 v[176:179], v168 offset:19456
	ds_read_b128 v[180:183], v168 offset:20480
	ds_read_b128 v[184:187], v168 offset:21504
	ds_read_b128 v[188:191], v168 offset:22528
	ds_read_b128 v[194:197], v168 offset:23552
	global_load_lds_dwordx4 v[220:221], off
	v_lshl_add_u64 v[222:223], s[28:29], 0, v[156:157]
	s_mov_b32 m0, s48
	s_nop 0
	global_load_lds_dwordx4 v[222:223], off
	s_barrier
	s_waitcnt lgkmcnt(0)
	s_setprio 1
	s_waitcnt lgkmcnt(0)
	v_mfma_f32_16x16x32_bf16 v[62:65], v[66:69], v[130:133], v[62:65]
	v_mfma_f32_16x16x32_bf16 v[54:57], v[74:77], v[130:133], v[54:57]
	v_mfma_f32_16x16x32_bf16 v[46:49], v[66:69], v[160:163], v[46:49]
	v_mfma_f32_16x16x32_bf16 v[38:41], v[74:77], v[160:163], v[38:41]
	v_mfma_f32_16x16x32_bf16 v[30:33], v[66:69], v[180:183], v[30:33]
	v_mfma_f32_16x16x32_bf16 v[22:25], v[74:77], v[180:183], v[22:25]
	v_mfma_f32_16x16x32_bf16 v[14:17], v[66:69], v[188:191], v[14:17]
	v_mfma_f32_16x16x32_bf16 v[6:9], v[74:77], v[188:191], v[6:9]
	v_mfma_f32_16x16x32_bf16 v[62:65], v[70:73], v[138:141], v[62:65]
	v_mfma_f32_16x16x32_bf16 v[54:57], v[78:81], v[138:141], v[54:57]
	v_mfma_f32_16x16x32_bf16 v[46:49], v[70:73], v[176:179], v[46:49]
	v_mfma_f32_16x16x32_bf16 v[38:41], v[78:81], v[176:179], v[38:41]
	v_mfma_f32_16x16x32_bf16 v[30:33], v[70:73], v[184:187], v[30:33]
	v_mfma_f32_16x16x32_bf16 v[22:25], v[78:81], v[184:187], v[22:25]
	v_mfma_f32_16x16x32_bf16 v[14:17], v[70:73], v[194:197], v[14:17]
	v_mfma_f32_16x16x32_bf16 v[6:9], v[78:81], v[194:197], v[6:9]
	s_setprio 0
	s_barrier
; #define PG8_STAGE(bufoff, gbase, voff) do { _Pragma("unroll") for (int _i = 0; _i < 2; ++_i) \
;         __builtin_amdgcn_global_load_lds((const unsigned*)((const char*)(gbase) + (voff)[_i]), (LAS unsigned*)(lds + (bufoff) + ldsw + _i * 8192), 16, 0, 0); } while (0)
; #define PG8_LDA(dst, b, h) do { _Pragma("unroll") for (int m = 0; m < 4; ++m) _Pragma("unroll") for (int k = 0; k < 2; ++k) dst[m][k] = *(const LAS bf16x8*)(lds + PG8_SA(b, h) + aoff + m * 2048 + k * 1024); } while (0)
; #define PG8_LDB(dst, b, h) do { _Pragma("unroll") for (int n = 0; n < 2; ++n) _Pragma("unroll") for (int k = 0; k < 2; ++k) dst[n][k] = *(const LAS bf16x8*)(lds + PG8_SB(b, h) + boff + n * 2048 + k * 1024); } while (0)
; #define PG8_MMA(ai, bj, At, Bt) do { __builtin_amdgcn_s_setprio(1); _Pragma("unroll") for (int m = 0; m < 4; ++m) _Pragma("unroll") for (int n = 0; n < 2; ++n) _Pragma("unroll") for (int k = 0; k < 2; ++k) \
;         acc[ai][bj][m][n] = __builtin_amdgcn_mfma_f32_16x16x32_bf16(Bt[n][k], At[m][k], acc[ai][bj][m][n], 0, 0, 0); __builtin_amdgcn_s_setprio(0); } while (0)
; #define PG8_WAIT_V(n) asm volatile("s_waitcnt vmcnt(" #n ")" ::: "memory")
; #define PG8_WAIT_L(n) asm volatile("s_waitcnt lgkmcnt(" #n ")" ::: "memory")
; #define PG8_BAR __builtin_amdgcn_s_barrier()
; #define PG8_SCHED __builtin_amdgcn_sched_barrier(0)
; template <class Epi, int KK, int LDA, int LDB, int NN, bool AGRP>
; __device__ __forceinline__ void gemm_phase(LAS unsigned char* lds, const bf16_t* gA, const bf16_t* gBt, int G_, int bid_, int tid) {
;     ...
;             PG8_STAGE(PG8_SB(0, 1), b2 + hstepB, voffB);
;             PG8_WAIT_V(6); PG8_BAR; PG8_MMA(1, 1, At, B1); PG8_BAR;
;             PG8_LDB(B0, 1, 0); PG8_SCHED; PG8_LDA(At, 1, 0); PG8_STAGE(PG8_SA(0, 1), a2 + hstepA, voffA);
;             PG8_WAIT_L(8); PG8_BAR; PG8_WAIT_L(0); PG8_MMA(0, 0, At, B0); PG8_BAR; PG8_SCHED;
;             PG8_LDB(B1, 1, 1); PG8_STAGE(PG8_SB(1, 0), b3, voffB);
;             PG8_BAR; PG8_WAIT_L(0); PG8_MMA(0, 1, At, B1); PG8_BAR;
;             PG8_LDA(At, 1, 1); PG8_STAGE(PG8_SA(1, 0), a3, voffA);
	s_mov_b32 m0, s50
	v_lshl_add_u64 v[66:67], s[26:27], 0, v[4:5]
	global_load_lds_dwordx4 v[66:67], off
	v_lshl_add_u64 v[66:67], s[26:27], 0, v[154:155]
	s_mov_b32 m0, s51
	s_nop 0
	global_load_lds_dwordx4 v[66:67], off
	s_waitcnt vmcnt(6)
	s_barrier
	s_setprio 1
	v_mfma_f32_16x16x32_bf16 v[58:61], v[200:203], v[130:133], v[58:61]
	v_mfma_f32_16x16x32_bf16 v[50:53], v[208:211], v[130:133], v[50:53]
	v_mfma_f32_16x16x32_bf16 v[42:45], v[200:203], v[160:163], v[42:45]
	v_mfma_f32_16x16x32_bf16 v[34:37], v[208:211], v[160:163], v[34:37]
	v_mfma_f32_16x16x32_bf16 v[26:29], v[200:203], v[180:183], v[26:29]
	v_mfma_f32_16x16x32_bf16 v[18:21], v[208:211], v[180:183], v[18:21]
	v_mfma_f32_16x16x32_bf16 v[10:13], v[200:203], v[188:191], v[10:13]
	v_mfma_f32_16x16x32_bf16 v[0:3], v[208:211], v[188:191], v[0:3]
	v_mfma_f32_16x16x32_bf16 v[58:61], v[204:207], v[138:141], v[58:61]
	v_mfma_f32_16x16x32_bf16 v[50:53], v[212:215], v[138:141], v[50:53]
	v_mfma_f32_16x16x32_bf16 v[42:45], v[204:207], v[176:179], v[42:45]
	v_mfma_f32_16x16x32_bf16 v[34:37], v[212:215], v[176:179], v[34:37]
	v_mfma_f32_16x16x32_bf16 v[26:29], v[204:207], v[184:187], v[26:29]
	v_mfma_f32_16x16x32_bf16 v[18:21], v[212:215], v[184:187], v[18:21]
	v_mfma_f32_16x16x32_bf16 v[10:13], v[204:207], v[194:197], v[10:13]
	v_mfma_f32_16x16x32_bf16 v[0:3], v[212:215], v[194:197], v[0:3]
	s_setprio 0
	v_add_u32_e32 v78, s54, v166
	s_barrier
	ds_read_b128 v[66:69], v78
	ds_read_b128 v[70:73], v78 offset:1024
	ds_read_b128 v[74:77], v78 offset:2048
	ds_read_b128 v[78:81], v78 offset:3072
	s_mov_b32 m0, s52
	v_lshl_add_u64 v[200:201], s[24:25], 0, v[158:159]
	ds_read_b128 v[130:133], v168 offset:32768
	ds_read_b128 v[138:141], v168 offset:33792
	ds_read_b128 v[160:163], v168 offset:34816
	ds_read_b128 v[176:179], v168 offset:35840
	ds_read_b128 v[180:183], v168 offset:36864
	ds_read_b128 v[184:187], v168 offset:37888
	ds_read_b128 v[188:191], v168 offset:38912
	ds_read_b128 v[194:197], v168 offset:39936
	global_load_lds_dwordx4 v[200:201], off
	v_lshl_add_u64 v[200:201], s[24:25], 0, v[156:157]
	s_mov_b32 m0, s53
	s_nop 0
	global_load_lds_dwordx4 v[200:201], off
	s_waitcnt lgkmcnt(8)
	s_barrier
	s_waitcnt lgkmcnt(0)
	s_setprio 1
	s_waitcnt lgkmcnt(0)
	v_mfma_f32_16x16x32_bf16 v[150:153], v[66:69], v[130:133], v[150:153]
	v_mfma_f32_16x16x32_bf16 v[142:145], v[74:77], v[130:133], v[142:145]
	v_mfma_f32_16x16x32_bf16 v[134:137], v[66:69], v[160:163], v[134:137]
	v_mfma_f32_16x16x32_bf16 v[126:129], v[74:77], v[160:163], v[126:129]
	v_mfma_f32_16x16x32_bf16 v[118:121], v[66:69], v[180:183], v[118:121]
	v_mfma_f32_16x16x32_bf16 v[110:113], v[74:77], v[180:183], v[110:113]
	v_mfma_f32_16x16x32_bf16 v[102:105], v[66:69], v[188:191], v[102:105]
	v_mfma_f32_16x16x32_bf16 v[94:97], v[74:77], v[188:191], v[94:97]
	v_mfma_f32_16x16x32_bf16 v[150:153], v[70:73], v[138:141], v[150:153]
	v_mfma_f32_16x16x32_bf16 v[142:145], v[78:81], v[138:141], v[142:145]
	v_mfma_f32_16x16x32_bf16 v[134:137], v[70:73], v[176:179], v[134:137]
	v_mfma_f32_16x16x32_bf16 v[126:129], v[78:81], v[176:179], v[126:129]
	v_mfma_f32_16x16x32_bf16 v[118:121], v[70:73], v[184:187], v[118:121]
	v_mfma_f32_16x16x32_bf16 v[110:113], v[78:81], v[184:187], v[110:113]
	v_mfma_f32_16x16x32_bf16 v[102:105], v[70:73], v[194:197], v[102:105]
	v_mfma_f32_16x16x32_bf16 v[94:97], v[78:81], v[194:197], v[94:97]
	s_setprio 0
	s_barrier
	s_mov_b32 m0, s55
	v_add_u32_e32 v169, s59, v166
	v_lshl_add_u64 v[216:217], v[216:217], 0, s[76:77]
	ds_read_b128 v[200:203], v169
	ds_read_b128 v[204:207], v169 offset:1024
	ds_read_b128 v[208:211], v169 offset:2048
	ds_read_b128 v[212:215], v169 offset:3072
	global_load_lds_dwordx4 v[216:217], off
	v_lshl_add_u64 v[216:217], v[218:219], 0, s[76:77]
	s_mov_b32 m0, s56
	s_nop 0
	global_load_lds_dwordx4 v[216:217], off
	s_barrier
	s_waitcnt lgkmcnt(0)
	s_setprio 1
	s_waitcnt lgkmcnt(0)
	v_mfma_f32_16x16x32_bf16 v[146:149], v[200:203], v[130:133], v[146:149]
	v_mfma_f32_16x16x32_bf16 v[82:85], v[208:211], v[130:133], v[82:85]
	v_mfma_f32_16x16x32_bf16 v[146:149], v[204:207], v[138:141], v[146:149]
	v_mfma_f32_16x16x32_bf16 v[138:141], v[212:215], v[138:141], v[82:85]
	v_mfma_f32_16x16x32_bf16 v[82:85], v[200:203], v[160:163], v[86:89]
	v_mfma_f32_16x16x32_bf16 v[130:133], v[204:207], v[176:179], v[82:85]
	v_mfma_f32_16x16x32_bf16 v[82:85], v[208:211], v[160:163], v[122:125]
	v_mfma_f32_16x16x32_bf16 v[122:125], v[212:215], v[176:179], v[82:85]
	v_mfma_f32_16x16x32_bf16 v[82:85], v[200:203], v[180:183], v[114:117]
	v_mfma_f32_16x16x32_bf16 v[114:117], v[204:207], v[184:187], v[82:85]
	v_mfma_f32_16x16x32_bf16 v[82:85], v[208:211], v[180:183], v[106:109]
	v_mfma_f32_16x16x32_bf16 v[106:109], v[212:215], v[184:187], v[82:85]
	v_mfma_f32_16x16x32_bf16 v[82:85], v[200:203], v[188:191], v[98:101]
	v_mfma_f32_16x16x32_bf16 v[98:101], v[204:207], v[194:197], v[82:85]
	v_mfma_f32_16x16x32_bf16 v[82:85], v[208:211], v[188:191], v[90:93]
	v_mfma_f32_16x16x32_bf16 v[90:93], v[212:215], v[194:197], v[82:85]
	s_setprio 0
	s_mov_b32 m0, s57
	v_lshl_add_u64 v[216:217], v[220:221], 0, s[76:77]
	s_barrier
	s_nop 2
	ds_read_b128 v[82:85], v168 offset:49152
	ds_read_b128 v[86:89], v168 offset:50176
	ds_read_b128 v[160:163], v168 offset:51200
	ds_read_b128 v[176:179], v168 offset:52224
	ds_read_b128 v[180:183], v168 offset:53248
	ds_read_b128 v[184:187], v168 offset:54272
	ds_read_b128 v[188:191], v168 offset:55296
	ds_read_b128 v[194:197], v168 offset:56320
	global_load_lds_dwordx4 v[216:217], off
	v_lshl_add_u64 v[216:217], v[222:223], 0, s[76:77]
	s_mov_b32 m0, s58
	s_nop 0
	global_load_lds_dwordx4 v[216:217], off
	s_barrier
; #define PG8_STAGE(bufoff, gbase, voff) do { _Pragma("unroll") for (int _i = 0; _i < 2; ++_i) \
;         __builtin_amdgcn_global_load_lds((const unsigned*)((const char*)(gbase) + (voff)[_i]), (LAS unsigned*)(lds + (bufoff) + ldsw + _i * 8192), 16, 0, 0); } while (0)
; #define PG8_MMA(ai, bj, At, Bt) do { __builtin_amdgcn_s_setprio(1); _Pragma("unroll") for (int m = 0; m < 4; ++m) _Pragma("unroll") for (int n = 0; n < 2; ++n) _Pragma("unroll") for (int k = 0; k < 2; ++k) \
;         acc[ai][bj][m][n] = __builtin_amdgcn_mfma_f32_16x16x32_bf16(Bt[n][k], At[m][k], acc[ai][bj][m][n], 0, 0, 0); __builtin_amdgcn_s_setprio(0); } while (0)
; #define PG8_WAIT_V(n) asm volatile("s_waitcnt vmcnt(" #n ")" ::: "memory")
; template <class Epi, int KK, int LDA, int LDB, int NN, bool AGRP>
; __device__ __forceinline__ void gemm_phase(LAS unsigned char* lds, const bf16_t* gA, const bf16_t* gBt, int G_, int bid_, int tid) {
;     ...
;             PG8_BAR; PG8_WAIT_L(0); PG8_MMA(1, 0, At, B0); PG8_BAR; PG8_SCHED;
;             PG8_STAGE(PG8_SB(1, 1), b3 + hstepB, voffB);
;             PG8_WAIT_V(6); PG8_BAR; PG8_MMA(1, 1, At, B1); PG8_BAR;
;     __device__ __forceinline__ void operator()(const f32x4 (&acc)[2][2][4][2], const Unit& u, int wr, int wc, int fr, int fq, LAS unsigned char* lds) const {
;         const int grp = u.pn >> 1, d = grp >> 2, blk = grp & 3, c0 = blk * 256 + (u.pn & 1) * 128 + wc * 32 + 8 * fq;
;         const int row0 = u.pm * BM + wr * 64 + fr;
;         const bf16_t* xb = EPP(const bf16_t*, 0); bf16_t* LA = EPP(bf16_t*, 1 + d); bf16_t* BB = EPP(bf16_t*, 3 + d);
;         const float* bx = EPP(const float*, 5); const float* ba = EPP(const float*, 6); const float* lsp = EPP(const float*, 7);
;         f32x4 vbx[2], vba[2], vls[2];
; #pragma unroll
;         for (int n = 0; n < 2; ++n) { vbx[n] = *(const f32x4*)(bx + d * D + c0 + 4 * n); vba[n] = *(const f32x4*)(ba + d * D + c0 + 4 * n); vls[n] = *(const f32x4*)(lsp + d * D + c0 + 4 * n); }
; #pragma unroll
;         for (int ai = 0; ai < 2; ++ai)
; #pragma unroll
;             for (int m = 0; m < 4; ++m) { const int row = row0 + ai * HALF + m * 16; const size_t o = (size_t)row * D + c0;
;                 const bool first = d == 0 ? ((row & (LS - 1)) == 0 && row != LS) : ((row & (LS - 1)) == LS - 1 && row != LS - 1);
;                 const u32x4 xw = *(const u32x4*)(xb + o);
	s_waitcnt lgkmcnt(0)
	s_setprio 1
	s_waitcnt lgkmcnt(0)
	v_mfma_f32_16x16x32_bf16 v[62:65], v[66:69], v[82:85], v[62:65]
	v_mfma_f32_16x16x32_bf16 v[54:57], v[74:77], v[82:85], v[54:57]
	v_mfma_f32_16x16x32_bf16 v[46:49], v[66:69], v[160:163], v[46:49]
	v_mfma_f32_16x16x32_bf16 v[38:41], v[74:77], v[160:163], v[38:41]
	v_mfma_f32_16x16x32_bf16 v[30:33], v[66:69], v[180:183], v[30:33]
	v_mfma_f32_16x16x32_bf16 v[22:25], v[74:77], v[180:183], v[22:25]
	v_mfma_f32_16x16x32_bf16 v[14:17], v[66:69], v[188:191], v[14:17]
	v_mfma_f32_16x16x32_bf16 v[6:9], v[74:77], v[188:191], v[6:9]
	v_mfma_f32_16x16x32_bf16 v[62:65], v[70:73], v[86:89], v[62:65]
	v_mfma_f32_16x16x32_bf16 v[54:57], v[78:81], v[86:89], v[54:57]
	v_mfma_f32_16x16x32_bf16 v[46:49], v[70:73], v[176:179], v[46:49]
	v_mfma_f32_16x16x32_bf16 v[38:41], v[78:81], v[176:179], v[38:41]
	v_mfma_f32_16x16x32_bf16 v[30:33], v[70:73], v[184:187], v[30:33]
	v_mfma_f32_16x16x32_bf16 v[22:25], v[78:81], v[184:187], v[22:25]
	v_mfma_f32_16x16x32_bf16 v[14:17], v[70:73], v[194:197], v[14:17]
	v_mfma_f32_16x16x32_bf16 v[6:9], v[78:81], v[194:197], v[6:9]
	s_setprio 0
	s_barrier
	s_mov_b32 m0, s60
	v_lshl_add_u64 v[66:67], s[22:23], 0, v[4:5]
	global_load_lds_dwordx4 v[66:67], off
	v_lshl_add_u64 v[66:67], s[22:23], 0, v[154:155]
	s_mov_b32 m0, s61
	s_nop 0
	global_load_lds_dwordx4 v[66:67], off
	s_waitcnt vmcnt(6)
	s_barrier
	s_setprio 1
	v_mfma_f32_16x16x32_bf16 v[58:61], v[200:203], v[82:85], v[58:61]
	v_mfma_f32_16x16x32_bf16 v[50:53], v[208:211], v[82:85], v[50:53]
	v_mfma_f32_16x16x32_bf16 v[42:45], v[200:203], v[160:163], v[42:45]
	v_mfma_f32_16x16x32_bf16 v[34:37], v[208:211], v[160:163], v[34:37]
	v_mfma_f32_16x16x32_bf16 v[26:29], v[200:203], v[180:183], v[26:29]
	v_mfma_f32_16x16x32_bf16 v[18:21], v[208:211], v[180:183], v[18:21]
	v_mfma_f32_16x16x32_bf16 v[10:13], v[200:203], v[188:191], v[10:13]
	v_mfma_f32_16x16x32_bf16 v[0:3], v[208:211], v[188:191], v[0:3]
	v_mfma_f32_16x16x32_bf16 v[58:61], v[204:207], v[86:89], v[58:61]
	v_mfma_f32_16x16x32_bf16 v[50:53], v[212:215], v[86:89], v[50:53]
	v_mfma_f32_16x16x32_bf16 v[42:45], v[204:207], v[176:179], v[42:45]
	v_mfma_f32_16x16x32_bf16 v[34:37], v[212:215], v[176:179], v[34:37]
	v_mfma_f32_16x16x32_bf16 v[26:29], v[204:207], v[184:187], v[26:29]
	v_mfma_f32_16x16x32_bf16 v[18:21], v[212:215], v[184:187], v[18:21]
	v_mfma_f32_16x16x32_bf16 v[10:13], v[204:207], v[194:197], v[10:13]
	v_mfma_f32_16x16x32_bf16 v[0:3], v[212:215], v[194:197], v[0:3]
	s_setprio 0
	s_andn2_b64 vcc, exec, s[20:21]
	s_mov_b64 s[22:23], -1
	s_mov_b64 s[20:21], 0
	s_mov_b64 s[24:25], 0x100
	s_barrier
	s_cbranch_vccz .LBB1_281
	s_lshl_b32 s1, s34, 7
	s_and_b32 s7, s1, 0x380
	v_or_b32_e32 v68, s7, v167
	s_and_b32 s7, s34, -8
	v_mov_b32_e32 v66, s66
	s_add_i32 s7, s66, s7
	ds_read_b32 v66, v66
	v_mov_b32_e32 v67, s62
	v_mov_b32_e32 v69, s7
	ds_read_b32 v67, v67
	ds_read_b32 v169, v69 offset:8
	ds_read_b32 v175, v69 offset:12
	ds_read_b32 v180, v69 offset:24
	ds_read_b32 v181, v69 offset:28
	v_mov_b32_e32 v69, s63
	ds_read_b32 v69, v69
	s_waitcnt lgkmcnt(0)
	v_readfirstlane_b32 s20, v66
	v_mov_b32_e32 v66, s70
	ds_read_b32 v70, v66
	v_mov_b32_e32 v66, s71
	v_readfirstlane_b32 s7, v69
	ds_read_b32 v69, v66
	v_mov_b32_e32 v66, s72
	ds_read_b32 v71, v66
	v_lshl_add_u32 v160, s0, 8, v165
	s_and_b32 s0, s1, 0xfffffc00
	s_ashr_i32 s1, s0, 31
	v_ashrrev_i32_e32 v161, 31, v160
	s_lshl_b64 s[0:1], s[0:1], 2
	v_mov_b32_e32 v66, s73
	v_lshlrev_b64 v[162:163], 11, v[160:161]
	v_lshlrev_b32_e32 v161, 1, v68
	s_waitcnt lgkmcnt(0)
	v_readfirstlane_b32 s9, v70
	s_add_u32 s16, s7, s0
	v_readfirstlane_b32 s21, v67
	ds_read_b32 v72, v66
	v_mov_b32_e32 v66, s82
	v_or_b32_e32 v162, v162, v161
	s_addc_u32 s17, s9, s1
	v_readfirstlane_b32 s7, v69
	ds_read_b32 v73, v66
	v_lshl_add_u64 v[66:67], s[20:21], 0, v[162:163]
	v_readfirstlane_b32 s9, v71
	s_add_u32 s18, s7, s0
	global_load_dwordx4 v[176:179], v[66:67], off
	v_mov_b32_e32 v219, 0
	v_mov_b32_e32 v218, 0x8000
	v_lshl_add_u64 v[216:217], v[66:67], 0, v[218:219]
	global_load_dwordx4 v[184:187], v[216:217], off
	v_mov_b32_e32 v218, 0x10000
	v_lshl_add_u64 v[216:217], v[66:67], 0, v[218:219]
	global_load_dwordx4 v[188:191], v[216:217], off
	v_mov_b32_e32 v218, 0x18000
	v_lshl_add_u64 v[216:217], v[66:67], 0, v[218:219]
	global_load_dwordx4 v[194:197], v[216:217], off
	v_mov_b32_e32 v218, 0x40000
	v_lshl_add_u64 v[216:217], v[66:67], 0, v[218:219]
	global_load_dwordx4 v[200:203], v[216:217], off
	v_mov_b32_e32 v218, 0x48000
	v_lshl_add_u64 v[216:217], v[66:67], 0, v[218:219]
	global_load_dwordx4 v[204:207], v[216:217], off
	v_mov_b32_e32 v218, 0x50000
	v_lshl_add_u64 v[216:217], v[66:67], 0, v[218:219]
	global_load_dwordx4 v[208:211], v[216:217], off
	v_mov_b32_e32 v218, 0x58000
	v_lshl_add_u64 v[216:217], v[66:67], 0, v[218:219]
	global_load_dwordx4 v[212:215], v[216:217], off
	v_lshlrev_b32_e32 v66, 2, v68
	s_addc_u32 s19, s9, s1
	global_load_dwordx4 v[78:81], v66, s[16:17]
	global_load_dwordx4 v[86:89], v66, s[18:19]
	s_waitcnt lgkmcnt(0)
	v_readfirstlane_b32 s7, v72
	v_readfirstlane_b32 s9, v73
	s_add_u32 s0, s7, s0
	s_addc_u32 s1, s9, s1
	global_load_dwordx4 v[82:85], v66, s[0:1]
	global_load_dwordx4 v[70:73], v66, s[16:17] offset:16
	global_load_dwordx4 v[74:77], v66, s[18:19] offset:16
	s_nop 0
	global_load_dwordx4 v[66:69], v66, s[0:1] offset:16
	v_and_b32_e32 v182, 0x1fcf, v160
	v_cmp_eq_u32_e64 s[0:1], 0, v182
	s_movk_i32 s7, 0x2000
	v_cmp_ne_u32_e32 vcc, s7, v160
	s_cmp_lt_u32 s34, 8
	s_cselect_b64 s[22:23], -1, 0
	s_and_b64 s[0:1], vcc, s[0:1]
	s_and_b64 s[0:1], s[22:23], s[0:1]
	v_readfirstlane_b32 s18, v169
	v_readfirstlane_b32 s19, v175
	v_readfirstlane_b32 s16, v180
	v_readfirstlane_b32 s17, v181
	s_movk_i32 s9, 0x1fff
	s_mov_b32 s34, s8
	s_waitcnt vmcnt(0)
; __device__ __forceinline__ unsigned cvt_pk_bf16(float lo, float hi) { unsigned r; asm volatile("v_cvt_pk_bf16_f32 %0, %1, %2" : "=v"(r) : "v"(lo), "v"(hi)); return r; }
; __device__ __forceinline__ float bflo(unsigned w) { return __uint_as_float(w << 16); }
; __device__ __forceinline__ float bfhi(unsigned w) { return __uint_as_float(w & 0xffff0000u); }
; __device__ __forceinline__ float fast_sigmoid(float x) { return __builtin_amdgcn_rcpf(1.0f + __builtin_amdgcn_exp2f(-1.44269504089f * x)); }
; __device__ __forceinline__ float fast_exp(float x) { return __builtin_amdgcn_exp2f(1.44269504089f * x); }
;     __device__ __forceinline__ void operator()(const f32x4 (&acc)[2][2][4][2], const Unit& u, int wr, int wc, int fr, int fq, LAS unsigned char* lds) const {
;     ...
;             for (int m = 0; m < 4; ++m) { const int row = row0 + ai * HALF + m * 16; const size_t o = (size_t)row * D + c0;
;                 const bool first = d == 0 ? ((row & (LS - 1)) == 0 && row != LS) : ((row & (LS - 1)) == LS - 1 && row != LS - 1);
;                 const u32x4 xw = *(const u32x4*)(xb + o);
;                 const float xv[8] = {bflo(xw.x), bfhi(xw.x), bflo(xw.y), bfhi(xw.y), bflo(xw.z), bfhi(xw.z), bflo(xw.w), bfhi(xw.w)};
;                 float lo[8], bo[8];
; #pragma unroll
;                 for (int n = 0; n < 2; ++n)
; #pragma unroll
;                     for (int e = 0; e < 4; ++e) { const int qd = 4 * n + e; const float gx = fast_sigmoid(acc[ai][0][m][n][e] + vbx[n][e]), ga = fast_sigmoid(acc[ai][1][m][n][e] + vba[n][e]);
;                         const float l = ga * vls[n][e]; const float mult = first ? 1.0f : __builtin_amdgcn_sqrtf(fmaxf(1.0f - fast_exp(2.0f * l), 0.f)); lo[qd] = l; bo[qd] = mult * gx * xv[qd]; }
;                 u32x4 w; w.x = cvt_pk_bf16(lo[0], lo[1]); w.y = cvt_pk_bf16(lo[2], lo[3]); w.z = cvt_pk_bf16(lo[4], lo[5]); w.w = cvt_pk_bf16(lo[6], lo[7]); *(u32x4*)(LA + o) = w;
;                 w.x = cvt_pk_bf16(bo[0], bo[1]); w.y = cvt_pk_bf16(bo[2], bo[3]); w.z = cvt_pk_bf16(bo[4], bo[5]); w.w = cvt_pk_bf16(bo[6], bo[7]); *(u32x4*)(BB + o) = w; }
	v_lshlrev_b32_e32 v169, 16, v176
	v_and_b32_e32 v175, 0xffff0000, v176
	v_lshlrev_b32_e32 v180, 16, v178
	v_add_f32_e32 v150, v150, v78
	v_add_f32_e32 v146, v146, v86
	v_mul_f32_e32 v146, 0xbfb8aa3b, v146
	v_exp_f32_e32 v146, v146
	v_add_f32_e32 v148, v148, v88
	v_mul_f32_e32 v150, 0xbfb8aa3b, v150
	v_mul_f32_e32 v148, 0xbfb8aa3b, v148
	v_add_f32_e32 v146, 1.0, v146
	v_rcp_f32_e32 v146, v146
	v_exp_f32_e32 v150, v150
	v_exp_f32_e32 v148, v148
	v_add_f32_e32 v149, v149, v89
	v_mul_f32_e32 v146, v82, v146
	v_add_f32_e32 v182, v146, v146
	v_mul_f32_e32 v182, 0x3fb8aa3b, v182
	v_exp_f32_e32 v182, v182
	v_add_f32_e32 v150, 1.0, v150
	v_add_f32_e32 v148, 1.0, v148
	v_rcp_f32_e32 v150, v150
	v_sub_f32_e32 v182, 1.0, v182
	v_max_f32_e32 v182, 0, v182
	v_sqrt_f32_e32 v182, v182
	v_rcp_f32_e32 v148, v148
	v_add_f32_e32 v152, v152, v80
	v_mul_f32_e32 v149, 0xbfb8aa3b, v149
	v_cndmask_b32_e64 v182, v182, 1.0, s[0:1]
	v_mul_f32_e32 v150, v150, v182
	v_mul_f32_e32 v148, v84, v148
	v_mul_f32_e32 v150, v150, v169
	v_add_f32_e32 v169, v148, v148
	v_mul_f32_e32 v169, 0x3fb8aa3b, v169
	v_exp_f32_e32 v169, v169
	v_mul_f32_e32 v152, 0xbfb8aa3b, v152
	v_exp_f32_e32 v149, v149
	v_exp_f32_e32 v152, v152
	v_sub_f32_e32 v169, 1.0, v169
	v_max_f32_e32 v169, 0, v169
	v_add_f32_e32 v149, 1.0, v149
	v_add_f32_e32 v152, 1.0, v152
	v_sqrt_f32_e32 v169, v169
	v_rcp_f32_e32 v149, v149
	v_rcp_f32_e32 v152, v152
	v_add_f32_e32 v153, v153, v81
	v_cndmask_b32_e64 v169, v169, 1.0, s[0:1]
	v_mul_f32_e32 v149, v85, v149
	v_mul_f32_e32 v152, v152, v169
	v_add_f32_e32 v169, v149, v149
	v_mul_f32_e32 v169, 0x3fb8aa3b, v169
	v_exp_f32_e32 v169, v169
	v_add_f32_e32 v138, v138, v74
	v_mul_f32_e32 v153, 0xbfb8aa3b, v153
	v_mul_f32_e32 v138, 0xbfb8aa3b, v138
	v_exp_f32_e32 v153, v153
	v_exp_f32_e32 v138, v138
	v_sub_f32_e32 v169, 1.0, v169
	v_max_f32_e32 v169, 0, v169
	v_sqrt_f32_e32 v169, v169
	v_add_f32_e32 v153, 1.0, v153
	v_add_f32_e32 v138, 1.0, v138
	v_rcp_f32_e32 v153, v153
	v_rcp_f32_e32 v138, v138
	v_add_f32_e32 v147, v147, v87
	v_mul_f32_e32 v147, 0xbfb8aa3b, v147
	v_exp_f32_e32 v147, v147
	v_cndmask_b32_e64 v169, v169, 1.0, s[0:1]
	v_mul_f32_e32 v153, v153, v169
	v_mul_f32_e32 v169, v66, v138
	v_add_f32_e32 v138, v169, v169
	v_mul_f32_e32 v138, 0x3fb8aa3b, v138
	v_add_f32_e32 v147, 1.0, v147
	v_add_f32_e32 v142, v142, v70
	v_exp_f32_e32 v138, v138
	v_add_f32_e32 v139, v139, v75
	v_rcp_f32_e32 v147, v147
	v_mul_f32_e32 v142, 0xbfb8aa3b, v142
	v_mul_f32_e32 v139, 0xbfb8aa3b, v139
	v_exp_f32_e32 v142, v142
	v_exp_f32_e32 v139, v139
	v_sub_f32_e32 v138, 1.0, v138
	v_mul_f32_e32 v147, v83, v147
	v_max_f32_e32 v138, 0, v138
	v_add_f32_e32 v183, v147, v147
	v_add_f32_e32 v142, 1.0, v142
	v_sqrt_f32_e32 v138, v138
	v_add_f32_e32 v139, 1.0, v139
	v_mul_f32_e32 v183, 0x3fb8aa3b, v183
	v_rcp_f32_e32 v142, v142
	v_rcp_f32_e32 v139, v139
	v_add_f32_e32 v151, v151, v79
	v_exp_f32_e32 v183, v183
	v_mul_f32_e32 v151, 0xbfb8aa3b, v151
	v_exp_f32_e32 v151, v151
	v_cndmask_b32_e64 v138, v138, 1.0, s[0:1]
	v_mul_f32_e32 v138, v142, v138
	v_mul_f32_e32 v142, v67, v139
	v_sub_f32_e32 v183, 1.0, v183
	v_add_f32_e32 v139, v142, v142
	v_max_f32_e32 v183, 0, v183
	v_mul_f32_e32 v139, 0x3fb8aa3b, v139
	v_add_f32_e32 v151, 1.0, v151
	v_sqrt_f32_e32 v183, v183
	v_exp_f32_e32 v139, v139
	v_add_f32_e32 v143, v143, v71
	v_rcp_f32_e32 v151, v151
	v_mul_f32_e32 v143, 0xbfb8aa3b, v143
	v_add_f32_e32 v140, v140, v76
	v_exp_f32_e32 v143, v143
	v_mul_f32_e32 v140, 0xbfb8aa3b, v140
	v_exp_f32_e32 v140, v140
	v_cndmask_b32_e64 v183, v183, 1.0, s[0:1]
	v_sub_f32_e32 v139, 1.0, v139
	v_mul_f32_e32 v151, v151, v183
	v_max_f32_e32 v139, 0, v139
	v_mul_f32_e32 v151, v151, v175
	v_sqrt_f32_e32 v139, v139
	v_mul_f32_e32 v175, v138, v180
	v_add_f32_e32 v138, 1.0, v143
	v_add_f32_e32 v143, v144, v72
	v_rcp_f32_e32 v138, v138
	v_mul_f32_e32 v143, 0xbfb8aa3b, v143
	v_add_f32_e32 v140, 1.0, v140
	v_exp_f32_e32 v143, v143
	v_rcp_f32_e32 v140, v140
	v_cndmask_b32_e64 v139, v139, 1.0, s[0:1]
	v_and_b32_e32 v178, 0xffff0000, v178
	v_mul_f32_e32 v138, v138, v139
	v_mul_f32_e32 v144, v138, v178
	v_add_f32_e32 v138, 1.0, v143
	v_mul_f32_e32 v143, v68, v140
	v_add_f32_e32 v140, v141, v77
	v_mul_f32_e32 v140, 0xbfb8aa3b, v140
	v_exp_f32_e32 v140, v140
	v_add_f32_e32 v139, v143, v143
	v_mul_f32_e32 v139, 0x3fb8aa3b, v139
	v_add_f32_e32 v141, v145, v73
	v_add_f32_e32 v140, 1.0, v140
	v_rcp_f32_e32 v140, v140
	v_exp_f32_e32 v139, v139
	v_mul_f32_e32 v141, 0xbfb8aa3b, v141
	v_exp_f32_e32 v141, v141
	v_mul_f32_e32 v145, v69, v140
	v_add_f32_e32 v140, v145, v145
	v_mul_f32_e32 v140, 0x3fb8aa3b, v140
	v_exp_f32_e32 v140, v140
	v_sub_f32_e32 v139, 1.0, v139
	v_max_f32_e32 v139, 0, v139
	v_sqrt_f32_e32 v139, v139
	v_sub_f32_e32 v140, 1.0, v140
	v_rcp_f32_e32 v138, v138
	v_max_f32_e32 v140, 0, v140
	v_add_f32_e32 v141, 1.0, v141
	v_sqrt_f32_e32 v140, v140
	v_rcp_f32_e32 v141, v141
	v_cndmask_b32_e64 v139, v139, 1.0, s[0:1]
	v_lshlrev_b32_e32 v176, 16, v177
	v_lshlrev_b32_e32 v181, 16, v179
	v_mul_f32_e32 v138, v138, v139
	v_mul_f32_e32 v152, v152, v176
	v_mul_f32_e32 v176, v138, v181
	v_cndmask_b32_e64 v138, v140, 1.0, s[0:1]
	v_and_b32_e32 v177, 0xffff0000, v177
	v_and_b32_e32 v179, 0xffff0000, v179
	v_mul_f32_e32 v138, v141, v138
	v_mul_f32_e32 v153, v153, v177
	v_mul_f32_e32 v177, v138, v179
	v_cvt_pk_bf16_f32 v138, v146, v147
	v_cvt_pk_bf16_f32 v139, v148, v149
	v_cvt_pk_bf16_f32 v140, v169, v142
	v_cvt_pk_bf16_f32 v141, v143, v145
	v_lshl_add_u64 v[142:143], s[18:19], 0, v[162:163]
	global_store_dwordx4 v[142:143], v[138:141], off
	v_lshl_add_u64 v[142:143], s[16:17], 0, v[162:163]
	v_add_f32_e32 v130, v130, v86
	v_cvt_pk_bf16_f32 v138, v150, v151
; __device__ __forceinline__ unsigned cvt_pk_bf16(float lo, float hi) { unsigned r; asm volatile("v_cvt_pk_bf16_f32 %0, %1, %2" : "=v"(r) : "v"(lo), "v"(hi)); return r; }
; __device__ __forceinline__ float bflo(unsigned w) { return __uint_as_float(w << 16); }
; __device__ __forceinline__ float bfhi(unsigned w) { return __uint_as_float(w & 0xffff0000u); }
; __device__ __forceinline__ float fast_sigmoid(float x) { return __builtin_amdgcn_rcpf(1.0f + __builtin_amdgcn_exp2f(-1.44269504089f * x)); }
; __device__ __forceinline__ float fast_exp(float x) { return __builtin_amdgcn_exp2f(1.44269504089f * x); }
;     __device__ __forceinline__ void operator()(const f32x4 (&acc)[2][2][4][2], const Unit& u, int wr, int wc, int fr, int fq, LAS unsigned char* lds) const {
;     ...
;             for (int m = 0; m < 4; ++m) { const int row = row0 + ai * HALF + m * 16; const size_t o = (size_t)row * D + c0;
;                 const bool first = d == 0 ? ((row & (LS - 1)) == 0 && row != LS) : ((row & (LS - 1)) == LS - 1 && row != LS - 1);
;                 const u32x4 xw = *(const u32x4*)(xb + o);
;                 const float xv[8] = {bflo(xw.x), bfhi(xw.x), bflo(xw.y), bfhi(xw.y), bflo(xw.z), bfhi(xw.z), bflo(xw.w), bfhi(xw.w)};
;                 float lo[8], bo[8];
; #pragma unroll
;                 for (int n = 0; n < 2; ++n)
; #pragma unroll
;                     for (int e = 0; e < 4; ++e) { const int qd = 4 * n + e; const float gx = fast_sigmoid(acc[ai][0][m][n][e] + vbx[n][e]), ga = fast_sigmoid(acc[ai][1][m][n][e] + vba[n][e]);
;                         const float l = ga * vls[n][e]; const float mult = first ? 1.0f : __builtin_amdgcn_sqrtf(fmaxf(1.0f - fast_exp(2.0f * l), 0.f)); lo[qd] = l; bo[qd] = mult * gx * xv[qd]; }
;                 u32x4 w; w.x = cvt_pk_bf16(lo[0], lo[1]); w.y = cvt_pk_bf16(lo[2], lo[3]); w.z = cvt_pk_bf16(lo[4], lo[5]); w.w = cvt_pk_bf16(lo[6], lo[7]); *(u32x4*)(LA + o) = w;
;                 w.x = cvt_pk_bf16(bo[0], bo[1]); w.y = cvt_pk_bf16(bo[2], bo[3]); w.z = cvt_pk_bf16(bo[4], bo[5]); w.w = cvt_pk_bf16(bo[6], bo[7]); *(u32x4*)(BB + o) = w; }
	v_cvt_pk_bf16_f32 v139, v152, v153
	v_cvt_pk_bf16_f32 v140, v175, v144
	v_cvt_pk_bf16_f32 v141, v176, v177
	global_store_dwordx4 v[142:143], v[138:141], off
	v_mul_f32_e32 v130, 0xbfb8aa3b, v130
	v_exp_f32_e32 v130, v130
	v_or_b32_e32 v138, 16, v160
	v_ashrrev_i32_e32 v139, 31, v138
	v_lshlrev_b64 v[142:143], 11, v[138:139]
	v_or_b32_e32 v142, v142, v161
	v_lshl_add_u64 v[138:139], s[20:21], 0, v[142:143]
	v_mov_b32_e32 v138, v184
	v_mov_b32_e32 v139, v185
	v_mov_b32_e32 v140, v186
	v_mov_b32_e32 v141, v187
	v_add_f32_e32 v130, 1.0, v130
	v_add_f32_e32 v131, v131, v87
	v_rcp_f32_e32 v130, v130
	v_mul_f32_e32 v131, 0xbfb8aa3b, v131
	v_exp_f32_e32 v131, v131
	v_add_f32_e32 v134, v134, v78
	v_mul_f32_e32 v130, v82, v130
	v_add_f32_e32 v148, v130, v130
	v_add_f32_e32 v131, 1.0, v131
	v_mul_f32_e32 v148, 0x3fb8aa3b, v148
	v_rcp_f32_e32 v131, v131
	v_mul_f32_e32 v134, 0xbfb8aa3b, v134
	v_exp_f32_e32 v148, v148
	v_exp_f32_e32 v134, v134
	v_mul_f32_e32 v131, v83, v131
	v_add_f32_e32 v149, v131, v131
	v_sub_f32_e32 v148, 1.0, v148
	v_add_f32_e32 v133, v133, v89
	v_add_f32_e32 v134, 1.0, v134
	v_max_f32_e32 v148, 0, v148
	v_add_f32_e32 v135, v135, v79
	v_mul_f32_e32 v149, 0x3fb8aa3b, v149
	v_mul_f32_e32 v133, 0xbfb8aa3b, v133
	v_rcp_f32_e32 v134, v134
	v_sqrt_f32_e32 v148, v148
	v_mul_f32_e32 v135, 0xbfb8aa3b, v135
	v_exp_f32_e32 v149, v149
	v_exp_f32_e32 v133, v133
	v_exp_f32_e32 v135, v135
	v_mul_f32_e32 v134, v134, v148
	v_sub_f32_e32 v148, 1.0, v149
	v_add_f32_e32 v133, 1.0, v133
	v_add_f32_e32 v135, 1.0, v135
	v_max_f32_e32 v148, 0, v148
	v_rcp_f32_e32 v133, v133
	v_rcp_f32_e32 v135, v135
	v_sqrt_f32_e32 v148, v148
	v_add_f32_e32 v122, v122, v74
	v_mul_f32_e32 v122, 0xbfb8aa3b, v122
	v_mul_f32_e32 v133, v85, v133
	v_exp_f32_e32 v122, v122
	v_mul_f32_e32 v135, v135, v148
	v_add_f32_e32 v148, v133, v133
	v_add_f32_e32 v137, v137, v81
	v_mul_f32_e32 v148, 0x3fb8aa3b, v148
	v_mul_f32_e32 v137, 0xbfb8aa3b, v137
	v_exp_f32_e32 v148, v148
	v_add_f32_e32 v123, v123, v75
	v_exp_f32_e32 v137, v137
	v_add_f32_e32 v122, 1.0, v122
	v_mul_f32_e32 v123, 0xbfb8aa3b, v123
	v_rcp_f32_e32 v122, v122
	v_exp_f32_e32 v123, v123
	v_sub_f32_e32 v148, 1.0, v148
	v_add_f32_e32 v137, 1.0, v137
	v_max_f32_e32 v148, 0, v148
	v_rcp_f32_e32 v137, v137
	v_sqrt_f32_e32 v148, v148
	v_add_f32_e32 v123, 1.0, v123
	v_rcp_f32_e32 v123, v123
	v_add_f32_e32 v126, v126, v70
	v_mul_f32_e32 v126, 0xbfb8aa3b, v126
	v_mul_f32_e32 v137, v137, v148
	v_exp_f32_e32 v126, v126
	v_add_f32_e32 v127, v127, v71
	v_add_f32_e32 v124, v124, v76
	v_add_f32_e32 v132, v132, v88
	v_add_f32_e32 v126, 1.0, v126
	v_mul_f32_e32 v127, 0xbfb8aa3b, v127
	v_mul_f32_e32 v124, 0xbfb8aa3b, v124
	v_add_f32_e32 v125, v125, v77
	v_mul_f32_e32 v132, 0xbfb8aa3b, v132
	v_rcp_f32_e32 v126, v126
	v_exp_f32_e32 v127, v127
	v_exp_f32_e32 v124, v124
	v_mul_f32_e32 v125, 0xbfb8aa3b, v125
	v_exp_f32_e32 v132, v132
	v_exp_f32_e32 v125, v125
	v_add_f32_e32 v124, 1.0, v124
	s_nop 0
	v_lshlrev_b32_e32 v144, 16, v138
	v_and_b32_e32 v138, 0xffff0000, v138
	v_mul_f32_e32 v135, v135, v138
	v_mul_f32_e32 v138, v66, v122
	v_add_f32_e32 v122, v138, v138
	v_mul_f32_e32 v122, 0x3fb8aa3b, v122
	v_exp_f32_e32 v122, v122
	v_lshlrev_b32_e32 v145, 16, v139
	v_and_b32_e32 v139, 0xffff0000, v139
	v_mul_f32_e32 v137, v137, v139
	v_mul_f32_e32 v139, v67, v123
	v_add_f32_e32 v123, v139, v139
	v_sub_f32_e32 v122, 1.0, v122
	v_mul_f32_e32 v123, 0x3fb8aa3b, v123
	v_max_f32_e32 v122, 0, v122
	v_exp_f32_e32 v123, v123
	v_sqrt_f32_e32 v122, v122
	v_add_f32_e32 v132, 1.0, v132
	v_rcp_f32_e32 v124, v124
	v_sub_f32_e32 v123, 1.0, v123
	v_mul_f32_e32 v122, v126, v122
	v_add_f32_e32 v126, 1.0, v127
	v_max_f32_e32 v123, 0, v123
	v_rcp_f32_e32 v126, v126
	v_sqrt_f32_e32 v123, v123
	v_add_f32_e32 v127, v128, v72
	v_add_f32_e32 v125, 1.0, v125
	v_rcp_f32_e32 v132, v132
	v_mul_f32_e32 v127, 0xbfb8aa3b, v127
	v_rcp_f32_e32 v125, v125
	v_exp_f32_e32 v127, v127
	v_lshlrev_b32_e32 v146, 16, v140
	v_mul_f32_e32 v128, v122, v146
	v_mul_f32_e32 v122, v126, v123
	v_mul_f32_e32 v126, v68, v124
	v_mul_f32_e32 v132, v84, v132
	v_add_f32_e32 v124, v126, v126
	v_mul_f32_e32 v125, v69, v125
	v_mul_f32_e32 v134, v134, v144
	v_add_f32_e32 v144, v132, v132
	v_add_f32_e32 v123, 1.0, v127
	v_mul_f32_e32 v124, 0x3fb8aa3b, v124
	v_add_f32_e32 v127, v129, v73
	v_add_f32_e32 v129, v125, v125
	v_add_f32_e32 v136, v136, v80
	v_mul_f32_e32 v144, 0x3fb8aa3b, v144
	v_exp_f32_e32 v124, v124
	v_mul_f32_e32 v129, 0x3fb8aa3b, v129
	v_mul_f32_e32 v136, 0xbfb8aa3b, v136
	v_exp_f32_e32 v144, v144
	v_mul_f32_e32 v127, 0xbfb8aa3b, v127
	v_exp_f32_e32 v129, v129
	v_exp_f32_e32 v136, v136
	v_exp_f32_e32 v127, v127
	v_sub_f32_e32 v124, 1.0, v124
	v_sub_f32_e32 v144, 1.0, v144
	v_max_f32_e32 v124, 0, v124
	v_sub_f32_e32 v129, 1.0, v129
	v_add_f32_e32 v136, 1.0, v136
	v_max_f32_e32 v144, 0, v144
	v_rcp_f32_e32 v123, v123
	v_sqrt_f32_e32 v124, v124
	v_add_f32_e32 v127, 1.0, v127
	v_max_f32_e32 v129, 0, v129
	v_rcp_f32_e32 v136, v136
	v_sqrt_f32_e32 v144, v144
	v_rcp_f32_e32 v127, v127
	v_sqrt_f32_e32 v129, v129
	v_and_b32_e32 v140, 0xffff0000, v140
	v_lshlrev_b32_e32 v147, 16, v141
	v_mul_f32_e32 v140, v122, v140
	v_mul_f32_e32 v122, v123, v124
	v_and_b32_e32 v141, 0xffff0000, v141
	v_mul_f32_e32 v136, v136, v144
	v_mul_f32_e32 v144, v122, v147
	v_mul_f32_e32 v122, v127, v129
	v_mul_f32_e32 v129, v122, v141
	v_cvt_pk_bf16_f32 v122, v130, v131
	v_cvt_pk_bf16_f32 v123, v132, v133
	v_cvt_pk_bf16_f32 v124, v138, v139
	v_cvt_pk_bf16_f32 v125, v126, v125
	v_lshl_add_u64 v[126:127], s[18:19], 0, v[142:143]
	global_store_dwordx4 v[126:127], v[122:125], off
	v_lshl_add_u64 v[126:127], s[16:17], 0, v[142:143]
; __device__ __forceinline__ unsigned cvt_pk_bf16(float lo, float hi) { unsigned r; asm volatile("v_cvt_pk_bf16_f32 %0, %1, %2" : "=v"(r) : "v"(lo), "v"(hi)); return r; }
; __device__ __forceinline__ float bflo(unsigned w) { return __uint_as_float(w << 16); }
; __device__ __forceinline__ float bfhi(unsigned w) { return __uint_as_float(w & 0xffff0000u); }
; __device__ __forceinline__ float fast_sigmoid(float x) { return __builtin_amdgcn_rcpf(1.0f + __builtin_amdgcn_exp2f(-1.44269504089f * x)); }
; __device__ __forceinline__ float fast_exp(float x) { return __builtin_amdgcn_exp2f(1.44269504089f * x); }
;     __device__ __forceinline__ void operator()(const f32x4 (&acc)[2][2][4][2], const Unit& u, int wr, int wc, int fr, int fq, LAS unsigned char* lds) const {
;     ...
;             for (int m = 0; m < 4; ++m) { const int row = row0 + ai * HALF + m * 16; const size_t o = (size_t)row * D + c0;
;                 const bool first = d == 0 ? ((row & (LS - 1)) == 0 && row != LS) : ((row & (LS - 1)) == LS - 1 && row != LS - 1);
;                 const u32x4 xw = *(const u32x4*)(xb + o);
;                 const float xv[8] = {bflo(xw.x), bfhi(xw.x), bflo(xw.y), bfhi(xw.y), bflo(xw.z), bfhi(xw.z), bflo(xw.w), bfhi(xw.w)};
;                 float lo[8], bo[8];
; #pragma unroll
;                 for (int n = 0; n < 2; ++n)
; #pragma unroll
;                     for (int e = 0; e < 4; ++e) { const int qd = 4 * n + e; const float gx = fast_sigmoid(acc[ai][0][m][n][e] + vbx[n][e]), ga = fast_sigmoid(acc[ai][1][m][n][e] + vba[n][e]);
;                         const float l = ga * vls[n][e]; const float mult = first ? 1.0f : __builtin_amdgcn_sqrtf(fmaxf(1.0f - fast_exp(2.0f * l), 0.f)); lo[qd] = l; bo[qd] = mult * gx * xv[qd]; }
;                 u32x4 w; w.x = cvt_pk_bf16(lo[0], lo[1]); w.y = cvt_pk_bf16(lo[2], lo[3]); w.z = cvt_pk_bf16(lo[4], lo[5]); w.w = cvt_pk_bf16(lo[6], lo[7]); *(u32x4*)(LA + o) = w;
;                 w.x = cvt_pk_bf16(bo[0], bo[1]); w.y = cvt_pk_bf16(bo[2], bo[3]); w.z = cvt_pk_bf16(bo[4], bo[5]); w.w = cvt_pk_bf16(bo[6], bo[7]); *(u32x4*)(BB + o) = w; }
	v_mul_f32_e32 v136, v136, v145
	v_cvt_pk_bf16_f32 v122, v134, v135
	v_cvt_pk_bf16_f32 v123, v136, v137
	v_cvt_pk_bf16_f32 v124, v128, v140
	v_cvt_pk_bf16_f32 v125, v144, v129
	global_store_dwordx4 v[126:127], v[122:125], off
	v_add_f32_e32 v114, v114, v86
	v_mul_f32_e32 v114, 0xbfb8aa3b, v114
	v_or_b32_e32 v122, 32, v160
	v_ashrrev_i32_e32 v123, 31, v122
	v_lshlrev_b64 v[126:127], 11, v[122:123]
	v_or_b32_e32 v126, v126, v161
	v_lshl_add_u64 v[122:123], s[20:21], 0, v[126:127]
	v_mov_b32_e32 v122, v188
	v_mov_b32_e32 v123, v189
	v_mov_b32_e32 v124, v190
	v_mov_b32_e32 v125, v191
	v_exp_f32_e32 v114, v114
	v_add_f32_e32 v115, v115, v87
	v_mul_f32_e32 v115, 0xbfb8aa3b, v115
	v_exp_f32_e32 v115, v115
	v_add_f32_e32 v114, 1.0, v114
	v_rcp_f32_e32 v114, v114
	v_add_f32_e32 v118, v118, v78
	v_add_f32_e32 v115, 1.0, v115
	v_rcp_f32_e32 v115, v115
	v_mul_f32_e32 v114, v82, v114
	v_add_f32_e32 v132, v114, v114
	v_mul_f32_e32 v132, 0x3fb8aa3b, v132
	v_mul_f32_e32 v118, 0xbfb8aa3b, v118
	v_exp_f32_e32 v132, v132
	v_exp_f32_e32 v118, v118
	v_mul_f32_e32 v115, v83, v115
	v_add_f32_e32 v133, v115, v115
	v_sub_f32_e32 v132, 1.0, v132
	v_add_f32_e32 v117, v117, v89
	v_add_f32_e32 v118, 1.0, v118
	v_max_f32_e32 v132, 0, v132
	v_add_f32_e32 v119, v119, v79
	v_mul_f32_e32 v133, 0x3fb8aa3b, v133
	v_mul_f32_e32 v117, 0xbfb8aa3b, v117
	v_rcp_f32_e32 v118, v118
	v_sqrt_f32_e32 v132, v132
	v_mul_f32_e32 v119, 0xbfb8aa3b, v119
	v_exp_f32_e32 v133, v133
	v_exp_f32_e32 v117, v117
	v_exp_f32_e32 v119, v119
	v_mul_f32_e32 v118, v118, v132
	v_sub_f32_e32 v132, 1.0, v133
	v_add_f32_e32 v117, 1.0, v117
	v_add_f32_e32 v119, 1.0, v119
	v_max_f32_e32 v132, 0, v132
	v_rcp_f32_e32 v117, v117
	v_rcp_f32_e32 v119, v119
	v_sqrt_f32_e32 v132, v132
	v_add_f32_e32 v106, v106, v74
	v_mul_f32_e32 v106, 0xbfb8aa3b, v106
	v_mul_f32_e32 v117, v85, v117
	v_exp_f32_e32 v106, v106
	v_mul_f32_e32 v119, v119, v132
	v_add_f32_e32 v132, v117, v117
	v_add_f32_e32 v121, v121, v81
	v_mul_f32_e32 v132, 0x3fb8aa3b, v132
	v_mul_f32_e32 v121, 0xbfb8aa3b, v121
	v_exp_f32_e32 v132, v132
	v_add_f32_e32 v107, v107, v75
	v_exp_f32_e32 v121, v121
	v_add_f32_e32 v106, 1.0, v106
	v_mul_f32_e32 v107, 0xbfb8aa3b, v107
	v_rcp_f32_e32 v106, v106
	v_exp_f32_e32 v107, v107
	v_sub_f32_e32 v132, 1.0, v132
	v_add_f32_e32 v121, 1.0, v121
	v_max_f32_e32 v132, 0, v132
	v_rcp_f32_e32 v121, v121
	v_sqrt_f32_e32 v132, v132
	v_add_f32_e32 v107, 1.0, v107
	v_rcp_f32_e32 v107, v107
	v_add_f32_e32 v110, v110, v70
	v_mul_f32_e32 v110, 0xbfb8aa3b, v110
	v_mul_f32_e32 v121, v121, v132
	v_exp_f32_e32 v110, v110
	v_add_f32_e32 v111, v111, v71
	v_add_f32_e32 v108, v108, v76
	v_add_f32_e32 v116, v116, v88
	v_add_f32_e32 v110, 1.0, v110
	v_mul_f32_e32 v111, 0xbfb8aa3b, v111
	v_mul_f32_e32 v108, 0xbfb8aa3b, v108
	v_add_f32_e32 v109, v109, v77
	v_mul_f32_e32 v116, 0xbfb8aa3b, v116
	v_rcp_f32_e32 v110, v110
	v_exp_f32_e32 v111, v111
	v_exp_f32_e32 v108, v108
	v_mul_f32_e32 v109, 0xbfb8aa3b, v109
	v_exp_f32_e32 v116, v116
	v_exp_f32_e32 v109, v109
	s_nop 0
	v_lshlrev_b32_e32 v128, 16, v122
	v_and_b32_e32 v122, 0xffff0000, v122
	v_mul_f32_e32 v119, v119, v122
	v_mul_f32_e32 v122, v66, v106
	v_add_f32_e32 v106, v122, v122
	v_mul_f32_e32 v106, 0x3fb8aa3b, v106
	v_exp_f32_e32 v106, v106
	v_lshlrev_b32_e32 v129, 16, v123
	v_and_b32_e32 v123, 0xffff0000, v123
	v_mul_f32_e32 v121, v121, v123
	v_mul_f32_e32 v123, v67, v107
	v_add_f32_e32 v107, v123, v123
	v_sub_f32_e32 v106, 1.0, v106
	v_mul_f32_e32 v107, 0x3fb8aa3b, v107
	v_max_f32_e32 v106, 0, v106
	v_exp_f32_e32 v107, v107
	v_sqrt_f32_e32 v106, v106
	v_add_f32_e32 v108, 1.0, v108
	v_add_f32_e32 v116, 1.0, v116
	v_sub_f32_e32 v107, 1.0, v107
	v_mul_f32_e32 v106, v110, v106
	v_add_f32_e32 v110, 1.0, v111
	v_max_f32_e32 v107, 0, v107
	v_rcp_f32_e32 v110, v110
	v_sqrt_f32_e32 v107, v107
	v_add_f32_e32 v111, v112, v72
	v_rcp_f32_e32 v108, v108
	v_add_f32_e32 v109, 1.0, v109
	v_rcp_f32_e32 v116, v116
	v_mul_f32_e32 v111, 0xbfb8aa3b, v111
	v_rcp_f32_e32 v109, v109
	v_exp_f32_e32 v111, v111
	v_lshlrev_b32_e32 v130, 16, v124
	v_mul_f32_e32 v112, v106, v130
	v_mul_f32_e32 v106, v110, v107
	v_mul_f32_e32 v110, v68, v108
	v_mul_f32_e32 v116, v84, v116
	v_add_f32_e32 v108, v110, v110
	v_mul_f32_e32 v109, v69, v109
	v_mul_f32_e32 v118, v118, v128
	v_add_f32_e32 v128, v116, v116
	v_add_f32_e32 v107, 1.0, v111
	v_mul_f32_e32 v108, 0x3fb8aa3b, v108
	v_add_f32_e32 v111, v113, v73
	v_add_f32_e32 v113, v109, v109
	v_add_f32_e32 v120, v120, v80
	v_mul_f32_e32 v128, 0x3fb8aa3b, v128
	v_exp_f32_e32 v108, v108
	v_mul_f32_e32 v113, 0x3fb8aa3b, v113
	v_mul_f32_e32 v120, 0xbfb8aa3b, v120
	v_exp_f32_e32 v128, v128
	v_mul_f32_e32 v111, 0xbfb8aa3b, v111
	v_exp_f32_e32 v113, v113
	v_exp_f32_e32 v120, v120
	v_exp_f32_e32 v111, v111
	v_sub_f32_e32 v108, 1.0, v108
	v_sub_f32_e32 v128, 1.0, v128
	v_max_f32_e32 v108, 0, v108
	v_sub_f32_e32 v113, 1.0, v113
	v_add_f32_e32 v120, 1.0, v120
	v_max_f32_e32 v128, 0, v128
	v_rcp_f32_e32 v107, v107
	v_sqrt_f32_e32 v108, v108
	v_add_f32_e32 v111, 1.0, v111
	v_max_f32_e32 v113, 0, v113
	v_rcp_f32_e32 v120, v120
	v_sqrt_f32_e32 v128, v128
	v_rcp_f32_e32 v111, v111
	v_sqrt_f32_e32 v113, v113
	v_and_b32_e32 v124, 0xffff0000, v124
	v_lshlrev_b32_e32 v131, 16, v125
	v_mul_f32_e32 v124, v106, v124
	v_mul_f32_e32 v106, v107, v108
	v_and_b32_e32 v125, 0xffff0000, v125
	v_mul_f32_e32 v120, v120, v128
	v_mul_f32_e32 v128, v106, v131
	v_mul_f32_e32 v106, v111, v113
	v_mul_f32_e32 v113, v106, v125
	v_cvt_pk_bf16_f32 v106, v114, v115
	v_cvt_pk_bf16_f32 v107, v116, v117
	v_cvt_pk_bf16_f32 v108, v122, v123
	v_cvt_pk_bf16_f32 v109, v110, v109
	v_lshl_add_u64 v[110:111], s[18:19], 0, v[126:127]
; __device__ __forceinline__ unsigned cvt_pk_bf16(float lo, float hi) { unsigned r; asm volatile("v_cvt_pk_bf16_f32 %0, %1, %2" : "=v"(r) : "v"(lo), "v"(hi)); return r; }
; __device__ __forceinline__ float bflo(unsigned w) { return __uint_as_float(w << 16); }
; __device__ __forceinline__ float bfhi(unsigned w) { return __uint_as_float(w & 0xffff0000u); }
; __device__ __forceinline__ float fast_sigmoid(float x) { return __builtin_amdgcn_rcpf(1.0f + __builtin_amdgcn_exp2f(-1.44269504089f * x)); }
; __device__ __forceinline__ float fast_exp(float x) { return __builtin_amdgcn_exp2f(1.44269504089f * x); }
;     __device__ __forceinline__ void operator()(const f32x4 (&acc)[2][2][4][2], const Unit& u, int wr, int wc, int fr, int fq, LAS unsigned char* lds) const {
;     ...
;             for (int m = 0; m < 4; ++m) { const int row = row0 + ai * HALF + m * 16; const size_t o = (size_t)row * D + c0;
;                 const bool first = d == 0 ? ((row & (LS - 1)) == 0 && row != LS) : ((row & (LS - 1)) == LS - 1 && row != LS - 1);
;                 const u32x4 xw = *(const u32x4*)(xb + o);
;                 const float xv[8] = {bflo(xw.x), bfhi(xw.x), bflo(xw.y), bfhi(xw.y), bflo(xw.z), bfhi(xw.z), bflo(xw.w), bfhi(xw.w)};
;                 float lo[8], bo[8];
; #pragma unroll
;                 for (int n = 0; n < 2; ++n)
; #pragma unroll
;                     for (int e = 0; e < 4; ++e) { const int qd = 4 * n + e; const float gx = fast_sigmoid(acc[ai][0][m][n][e] + vbx[n][e]), ga = fast_sigmoid(acc[ai][1][m][n][e] + vba[n][e]);
;                         const float l = ga * vls[n][e]; const float mult = first ? 1.0f : __builtin_amdgcn_sqrtf(fmaxf(1.0f - fast_exp(2.0f * l), 0.f)); lo[qd] = l; bo[qd] = mult * gx * xv[qd]; }
;                 u32x4 w; w.x = cvt_pk_bf16(lo[0], lo[1]); w.y = cvt_pk_bf16(lo[2], lo[3]); w.z = cvt_pk_bf16(lo[4], lo[5]); w.w = cvt_pk_bf16(lo[6], lo[7]); *(u32x4*)(LA + o) = w;
;                 w.x = cvt_pk_bf16(bo[0], bo[1]); w.y = cvt_pk_bf16(bo[2], bo[3]); w.z = cvt_pk_bf16(bo[4], bo[5]); w.w = cvt_pk_bf16(bo[6], bo[7]); *(u32x4*)(BB + o) = w; }
	global_store_dwordx4 v[110:111], v[106:109], off
	v_lshl_add_u64 v[110:111], s[16:17], 0, v[126:127]
	v_mul_f32_e32 v120, v120, v129
	v_cvt_pk_bf16_f32 v106, v118, v119
	v_cvt_pk_bf16_f32 v107, v120, v121
	v_cvt_pk_bf16_f32 v108, v112, v124
	v_cvt_pk_bf16_f32 v109, v128, v113
	global_store_dwordx4 v[110:111], v[106:109], off
	v_add_f32_e32 v98, v98, v86
	v_mul_f32_e32 v98, 0xbfb8aa3b, v98
	v_or_b32_e32 v106, 48, v160
	v_ashrrev_i32_e32 v107, 31, v106
	v_lshlrev_b64 v[106:107], 11, v[106:107]
	v_or_b32_e32 v106, v106, v161
	v_lshl_add_u64 v[108:109], s[20:21], 0, v[106:107]
	v_mov_b32_e32 v108, v194
	v_mov_b32_e32 v109, v195
	v_mov_b32_e32 v110, v196
	v_mov_b32_e32 v111, v197
	v_exp_f32_e32 v98, v98
	v_add_f32_e32 v99, v99, v87
	v_add_f32_e32 v102, v102, v78
	v_mul_f32_e32 v99, 0xbfb8aa3b, v99
	v_add_f32_e32 v98, 1.0, v98
	v_rcp_f32_e32 v98, v98
	v_mul_f32_e32 v102, 0xbfb8aa3b, v102
	v_exp_f32_e32 v99, v99
	v_exp_f32_e32 v102, v102
	v_mul_f32_e32 v98, v82, v98
	v_add_f32_e32 v116, v98, v98
	v_mul_f32_e32 v116, 0x3fb8aa3b, v116
	v_exp_f32_e32 v116, v116
	v_add_f32_e32 v99, 1.0, v99
	v_bitop3_b32 v112, v160, s9, 48 bitop3:0xc8
	s_movk_i32 s0, 0x1fcf
	v_sub_f32_e32 v116, 1.0, v116
	v_max_f32_e32 v116, 0, v116
	v_add_f32_e32 v102, 1.0, v102
	v_sqrt_f32_e32 v116, v116
	v_rcp_f32_e32 v99, v99
	v_cmp_ne_u32_e32 vcc, s9, v112
	v_cmp_eq_u32_e64 s[0:1], s0, v160
	v_rcp_f32_e32 v102, v102
	s_or_b64 s[0:1], s[0:1], vcc
	s_or_b64 vcc, s[22:23], s[0:1]
	v_cndmask_b32_e32 v116, 1.0, v116, vcc
	v_mul_f32_e32 v99, v83, v99
	v_mul_f32_e32 v102, v102, v116
	v_add_f32_e32 v116, v99, v99
	v_mul_f32_e32 v116, 0x3fb8aa3b, v116
	v_add_f32_e32 v100, v100, v88
	v_exp_f32_e32 v116, v116
	v_add_f32_e32 v103, v103, v79
	v_mul_f32_e32 v100, 0xbfb8aa3b, v100
	v_mul_f32_e32 v103, 0xbfb8aa3b, v103
	v_exp_f32_e32 v100, v100
	v_exp_f32_e32 v103, v103
	v_sub_f32_e32 v116, 1.0, v116
	v_max_f32_e32 v116, 0, v116
	v_add_f32_e32 v100, 1.0, v100
	v_sqrt_f32_e32 v116, v116
	v_add_f32_e32 v103, 1.0, v103
	v_rcp_f32_e32 v100, v100
	v_rcp_f32_e32 v103, v103
	v_add_f32_e32 v101, v101, v89
	v_add_f32_e32 v104, v104, v80
	v_mul_f32_e32 v100, v84, v100
	v_mul_f32_e32 v101, 0xbfb8aa3b, v101
	v_mul_f32_e32 v104, 0xbfb8aa3b, v104
	v_exp_f32_e32 v101, v101
	v_exp_f32_e32 v104, v104
	v_add_f32_e32 v105, v105, v81
	v_add_f32_e32 v90, v90, v74
	v_add_f32_e32 v101, 1.0, v101
	v_add_f32_e32 v104, 1.0, v104
	v_rcp_f32_e32 v101, v101
	v_rcp_f32_e32 v104, v104
	v_mul_f32_e32 v105, 0xbfb8aa3b, v105
	v_mul_f32_e32 v90, 0xbfb8aa3b, v90
	v_mul_f32_e32 v101, v85, v101
	v_exp_f32_e32 v105, v105
	v_exp_f32_e32 v90, v90
	v_add_f32_e32 v94, v94, v70
	v_add_f32_e32 v91, v91, v75
	v_add_f32_e32 v105, 1.0, v105
	v_add_f32_e32 v90, 1.0, v90
	v_rcp_f32_e32 v105, v105
	v_rcp_f32_e32 v90, v90
	v_mul_f32_e32 v94, 0xbfb8aa3b, v94
	v_mul_f32_e32 v91, 0xbfb8aa3b, v91
	v_exp_f32_e32 v94, v94
	v_exp_f32_e32 v91, v91
	v_add_f32_e32 v95, v95, v71
	v_mul_f32_e32 v95, 0xbfb8aa3b, v95
	v_add_f32_e32 v94, 1.0, v94
	v_add_f32_e32 v91, 1.0, v91
	v_rcp_f32_e32 v94, v94
	v_rcp_f32_e32 v91, v91
	s_nop 0
	v_lshlrev_b32_e32 v112, 16, v108
	v_mul_f32_e32 v102, v102, v112
	v_cndmask_b32_e32 v112, 1.0, v116, vcc
	v_mul_f32_e32 v103, v103, v112
	v_add_f32_e32 v112, v100, v100
	v_mul_f32_e32 v112, 0x3fb8aa3b, v112
	v_exp_f32_e32 v112, v112
	v_and_b32_e32 v108, 0xffff0000, v108
	v_mul_f32_e32 v103, v103, v108
	v_add_f32_e32 v92, v92, v76
	v_sub_f32_e32 v112, 1.0, v112
	v_max_f32_e32 v112, 0, v112
	v_sqrt_f32_e32 v112, v112
	v_exp_f32_e32 v95, v95
	v_mul_f32_e32 v92, 0xbfb8aa3b, v92
	v_exp_f32_e32 v92, v92
	v_cndmask_b32_e32 v108, 1.0, v112, vcc
	v_mul_f32_e32 v104, v104, v108
	v_add_f32_e32 v108, v101, v101
	v_mul_f32_e32 v108, 0x3fb8aa3b, v108
	v_exp_f32_e32 v108, v108
	v_lshlrev_b32_e32 v113, 16, v109
	v_and_b32_e32 v109, 0xffff0000, v109
	v_lshlrev_b32_e32 v114, 16, v110
	v_sub_f32_e32 v108, 1.0, v108
	v_max_f32_e32 v108, 0, v108
	v_sqrt_f32_e32 v108, v108
	v_add_f32_e32 v92, 1.0, v92
	v_rcp_f32_e32 v92, v92
	v_and_b32_e32 v110, 0xffff0000, v110
	v_cndmask_b32_e32 v108, 1.0, v108, vcc
	v_mul_f32_e32 v105, v105, v108
	v_mul_f32_e32 v108, v66, v90
	v_add_f32_e32 v90, v108, v108
	v_mul_f32_e32 v90, 0x3fb8aa3b, v90
	v_exp_f32_e32 v90, v90
	v_mul_f32_e32 v105, v105, v109
	v_lshlrev_b32_e32 v115, 16, v111
	v_and_b32_e32 v111, 0xffff0000, v111
	v_sub_f32_e32 v90, 1.0, v90
	v_max_f32_e32 v90, 0, v90
	v_sqrt_f32_e32 v90, v90
	v_mul_f32_e32 v104, v104, v113
	v_add_f32_e32 v58, v58, v86
	v_mul_f32_e32 v58, 0xbfb8aa3b, v58
	v_cndmask_b32_e32 v90, 1.0, v90, vcc
	v_mul_f32_e32 v90, v94, v90
	v_mul_f32_e32 v94, v67, v91
	v_add_f32_e32 v91, v94, v94
	v_mul_f32_e32 v91, 0x3fb8aa3b, v91
	v_exp_f32_e32 v91, v91
	v_mul_f32_e32 v109, v90, v114
	v_add_f32_e32 v90, 1.0, v95
	v_add_f32_e32 v95, v96, v72
	v_sub_f32_e32 v91, 1.0, v91
	v_max_f32_e32 v91, 0, v91
	v_sqrt_f32_e32 v91, v91
	v_rcp_f32_e32 v90, v90
	v_mul_f32_e32 v95, 0xbfb8aa3b, v95
	v_exp_f32_e32 v95, v95
	v_cndmask_b32_e32 v91, 1.0, v91, vcc
	v_mul_f32_e32 v90, v90, v91
	v_mul_f32_e32 v96, v90, v110
	v_add_f32_e32 v90, 1.0, v95
	v_mul_f32_e32 v95, v68, v92
	v_add_f32_e32 v92, v93, v77
	v_mul_f32_e32 v92, 0xbfb8aa3b, v92
	v_exp_f32_e32 v92, v92
	v_add_f32_e32 v91, v95, v95
	v_mul_f32_e32 v91, 0x3fb8aa3b, v91
	v_add_f32_e32 v93, v97, v73
	v_add_f32_e32 v92, 1.0, v92
	v_rcp_f32_e32 v92, v92
	v_exp_f32_e32 v91, v91
	v_mul_f32_e32 v93, 0xbfb8aa3b, v93
	v_exp_f32_e32 v93, v93
	v_mul_f32_e32 v97, v69, v92
	v_add_f32_e32 v92, v97, v97
	v_mul_f32_e32 v92, 0x3fb8aa3b, v92
	v_exp_f32_e32 v92, v92
	v_sub_f32_e32 v91, 1.0, v91
	v_max_f32_e32 v91, 0, v91
	v_sqrt_f32_e32 v91, v91
	v_sub_f32_e32 v92, 1.0, v92
; __device__ __forceinline__ unsigned cvt_pk_bf16(float lo, float hi) { unsigned r; asm volatile("v_cvt_pk_bf16_f32 %0, %1, %2" : "=v"(r) : "v"(lo), "v"(hi)); return r; }
; __device__ __forceinline__ float bflo(unsigned w) { return __uint_as_float(w << 16); }
; __device__ __forceinline__ float bfhi(unsigned w) { return __uint_as_float(w & 0xffff0000u); }
; __device__ __forceinline__ float fast_sigmoid(float x) { return __builtin_amdgcn_rcpf(1.0f + __builtin_amdgcn_exp2f(-1.44269504089f * x)); }
; __device__ __forceinline__ float fast_exp(float x) { return __builtin_amdgcn_exp2f(1.44269504089f * x); }
;     __device__ __forceinline__ void operator()(const f32x4 (&acc)[2][2][4][2], const Unit& u, int wr, int wc, int fr, int fq, LAS unsigned char* lds) const {
;     ...
;             for (int m = 0; m < 4; ++m) { const int row = row0 + ai * HALF + m * 16; const size_t o = (size_t)row * D + c0;
;                 const bool first = d == 0 ? ((row & (LS - 1)) == 0 && row != LS) : ((row & (LS - 1)) == LS - 1 && row != LS - 1);
;                 const u32x4 xw = *(const u32x4*)(xb + o);
;                 const float xv[8] = {bflo(xw.x), bfhi(xw.x), bflo(xw.y), bfhi(xw.y), bflo(xw.z), bfhi(xw.z), bflo(xw.w), bfhi(xw.w)};
;                 float lo[8], bo[8];
; #pragma unroll
;                 for (int n = 0; n < 2; ++n)
; #pragma unroll
;                     for (int e = 0; e < 4; ++e) { const int qd = 4 * n + e; const float gx = fast_sigmoid(acc[ai][0][m][n][e] + vbx[n][e]), ga = fast_sigmoid(acc[ai][1][m][n][e] + vba[n][e]);
;                         const float l = ga * vls[n][e]; const float mult = first ? 1.0f : __builtin_amdgcn_sqrtf(fmaxf(1.0f - fast_exp(2.0f * l), 0.f)); lo[qd] = l; bo[qd] = mult * gx * xv[qd]; }
;                 u32x4 w; w.x = cvt_pk_bf16(lo[0], lo[1]); w.y = cvt_pk_bf16(lo[2], lo[3]); w.z = cvt_pk_bf16(lo[4], lo[5]); w.w = cvt_pk_bf16(lo[6], lo[7]); *(u32x4*)(LA + o) = w;
;                 w.x = cvt_pk_bf16(bo[0], bo[1]); w.y = cvt_pk_bf16(bo[2], bo[3]); w.z = cvt_pk_bf16(bo[4], bo[5]); w.w = cvt_pk_bf16(bo[6], bo[7]); *(u32x4*)(BB + o) = w; }
	v_rcp_f32_e32 v90, v90
	v_max_f32_e32 v92, 0, v92
	v_add_f32_e32 v93, 1.0, v93
	v_sqrt_f32_e32 v92, v92
	v_rcp_f32_e32 v93, v93
	v_cndmask_b32_e32 v91, 1.0, v91, vcc
	v_mul_f32_e32 v90, v90, v91
	v_mul_f32_e32 v110, v90, v115
	v_cndmask_b32_e32 v90, 1.0, v92, vcc
	v_mul_f32_e32 v90, v93, v90
	v_mul_f32_e32 v111, v90, v111
	v_cvt_pk_bf16_f32 v90, v98, v99
	v_cvt_pk_bf16_f32 v91, v100, v101
	v_cvt_pk_bf16_f32 v92, v108, v94
	v_cvt_pk_bf16_f32 v93, v95, v97
	v_lshl_add_u64 v[94:95], s[18:19], 0, v[106:107]
	global_store_dwordx4 v[94:95], v[90:93], off
	v_lshl_add_u64 v[94:95], s[16:17], 0, v[106:107]
	v_exp_f32_e32 v58, v58
	v_cvt_pk_bf16_f32 v90, v102, v103
	v_cvt_pk_bf16_f32 v91, v104, v105
	v_cvt_pk_bf16_f32 v92, v109, v96
	v_add_u32_e32 v96, 0x80, v160
	v_ashrrev_i32_e32 v97, 31, v96
	v_cvt_pk_bf16_f32 v93, v110, v111
	global_store_dwordx4 v[94:95], v[90:93], off
	v_add_f32_e32 v58, 1.0, v58
	v_rcp_f32_e32 v58, v58
	v_lshlrev_b64 v[90:91], 11, v[96:97]
	v_or_b32_e32 v90, v90, v161
	v_lshl_add_u64 v[92:93], s[20:21], 0, v[90:91]
	v_mov_b32_e32 v92, v200
	v_mov_b32_e32 v93, v201
	v_mov_b32_e32 v94, v202
	v_mov_b32_e32 v95, v203
	v_mul_f32_e32 v58, v82, v58
	v_add_f32_e32 v100, v58, v58
	v_mul_f32_e32 v100, 0x3fb8aa3b, v100
	v_add_f32_e32 v59, v59, v87
	v_add_f32_e32 v62, v62, v78
	v_exp_f32_e32 v100, v100
	v_mul_f32_e32 v59, 0xbfb8aa3b, v59
	v_mul_f32_e32 v62, 0xbfb8aa3b, v62
	v_exp_f32_e32 v59, v59
	v_exp_f32_e32 v62, v62
	v_sub_f32_e32 v100, 1.0, v100
	v_max_f32_e32 v100, 0, v100
	v_add_f32_e32 v59, 1.0, v59
	v_and_b32_e32 v97, 0x1fcf, v96
	v_add_f32_e32 v62, 1.0, v62
	v_sqrt_f32_e32 v100, v100
	v_rcp_f32_e32 v59, v59
	v_cmp_eq_u32_e32 vcc, 0, v97
	v_cmp_ne_u32_e64 s[0:1], s7, v96
	v_rcp_f32_e32 v62, v62
	s_and_b64 s[0:1], s[0:1], vcc
	s_and_b64 s[0:1], s[22:23], s[0:1]
	v_cndmask_b32_e64 v100, v100, 1.0, s[0:1]
	v_mul_f32_e32 v59, v83, v59
	v_mul_f32_e32 v62, v62, v100
	v_add_f32_e32 v100, v59, v59
	v_mul_f32_e32 v100, 0x3fb8aa3b, v100
	v_add_f32_e32 v60, v60, v88
	v_exp_f32_e32 v100, v100
	v_add_f32_e32 v63, v63, v79
	v_mul_f32_e32 v60, 0xbfb8aa3b, v60
	v_mul_f32_e32 v63, 0xbfb8aa3b, v63
	v_exp_f32_e32 v60, v60
	v_exp_f32_e32 v63, v63
	v_sub_f32_e32 v100, 1.0, v100
	v_max_f32_e32 v100, 0, v100
	v_add_f32_e32 v60, 1.0, v60
	v_sqrt_f32_e32 v100, v100
	v_add_f32_e32 v63, 1.0, v63
	v_rcp_f32_e32 v60, v60
	v_rcp_f32_e32 v63, v63
	v_add_f32_e32 v61, v61, v89
	v_add_f32_e32 v64, v64, v80
	v_mul_f32_e32 v60, v84, v60
	v_mul_f32_e32 v61, 0xbfb8aa3b, v61
	v_mul_f32_e32 v64, 0xbfb8aa3b, v64
	v_exp_f32_e32 v61, v61
	v_exp_f32_e32 v64, v64
	v_add_f32_e32 v65, v65, v81
	v_add_f32_e32 v50, v50, v74
	v_add_f32_e32 v61, 1.0, v61
	v_add_f32_e32 v64, 1.0, v64
	v_rcp_f32_e32 v61, v61
	v_rcp_f32_e32 v64, v64
	v_mul_f32_e32 v65, 0xbfb8aa3b, v65
	v_mul_f32_e32 v50, 0xbfb8aa3b, v50
	v_mul_f32_e32 v61, v85, v61
	v_exp_f32_e32 v65, v65
	v_exp_f32_e32 v50, v50
	v_add_f32_e32 v54, v54, v70
	v_add_f32_e32 v51, v51, v75
	v_add_f32_e32 v65, 1.0, v65
	v_add_f32_e32 v50, 1.0, v50
	v_rcp_f32_e32 v65, v65
	v_rcp_f32_e32 v50, v50
	v_mul_f32_e32 v54, 0xbfb8aa3b, v54
	v_mul_f32_e32 v51, 0xbfb8aa3b, v51
	v_exp_f32_e32 v54, v54
	v_exp_f32_e32 v51, v51
	v_add_f32_e32 v55, v55, v71
	v_mul_f32_e32 v55, 0xbfb8aa3b, v55
	v_add_f32_e32 v54, 1.0, v54
	v_add_f32_e32 v51, 1.0, v51
	v_rcp_f32_e32 v54, v54
	v_rcp_f32_e32 v51, v51
	v_add_f32_e32 v52, v52, v76
	v_exp_f32_e32 v55, v55
	v_mul_f32_e32 v52, 0xbfb8aa3b, v52
	v_exp_f32_e32 v52, v52
	s_nop 0
	v_lshlrev_b32_e32 v96, 16, v92
	v_mul_f32_e32 v62, v62, v96
	v_cndmask_b32_e64 v96, v100, 1.0, s[0:1]
	v_mul_f32_e32 v63, v63, v96
	v_add_f32_e32 v96, v60, v60
	v_mul_f32_e32 v96, 0x3fb8aa3b, v96
	v_exp_f32_e32 v96, v96
	v_and_b32_e32 v92, 0xffff0000, v92
	v_mul_f32_e32 v63, v63, v92
	v_lshlrev_b32_e32 v97, 16, v93
	v_sub_f32_e32 v96, 1.0, v96
	v_max_f32_e32 v96, 0, v96
	v_sqrt_f32_e32 v96, v96
	v_and_b32_e32 v93, 0xffff0000, v93
	v_lshlrev_b32_e32 v98, 16, v94
	v_add_f32_e32 v52, 1.0, v52
	v_cndmask_b32_e64 v92, v96, 1.0, s[0:1]
	v_mul_f32_e32 v64, v64, v92
	v_add_f32_e32 v92, v61, v61
	v_mul_f32_e32 v92, 0x3fb8aa3b, v92
	v_exp_f32_e32 v92, v92
	v_rcp_f32_e32 v52, v52
	v_and_b32_e32 v94, 0xffff0000, v94
	v_lshlrev_b32_e32 v99, 16, v95
	v_sub_f32_e32 v92, 1.0, v92
	v_max_f32_e32 v92, 0, v92
	v_sqrt_f32_e32 v92, v92
	v_and_b32_e32 v95, 0xffff0000, v95
	v_mul_f32_e32 v64, v64, v97
	v_add_f32_e32 v42, v42, v86
	v_cndmask_b32_e64 v92, v92, 1.0, s[0:1]
	v_mul_f32_e32 v65, v65, v92
	v_mul_f32_e32 v92, v66, v50
	v_add_f32_e32 v50, v92, v92
	v_mul_f32_e32 v50, 0x3fb8aa3b, v50
	v_exp_f32_e32 v50, v50
	v_mul_f32_e32 v65, v65, v93
	v_mul_f32_e32 v42, 0xbfb8aa3b, v42
	v_exp_f32_e32 v42, v42
	v_sub_f32_e32 v50, 1.0, v50
	v_max_f32_e32 v50, 0, v50
	v_sqrt_f32_e32 v50, v50
	v_add_f32_e32 v42, 1.0, v42
	v_add_f32_e32 v43, v43, v87
	v_rcp_f32_e32 v42, v42
	v_cndmask_b32_e64 v50, v50, 1.0, s[0:1]
	v_mul_f32_e32 v50, v54, v50
	v_mul_f32_e32 v54, v67, v51
	v_add_f32_e32 v51, v54, v54
	v_mul_f32_e32 v51, 0x3fb8aa3b, v51
	v_exp_f32_e32 v51, v51
	v_mul_f32_e32 v93, v50, v98
	v_add_f32_e32 v50, 1.0, v55
	v_add_f32_e32 v55, v56, v72
	v_sub_f32_e32 v51, 1.0, v51
	v_max_f32_e32 v51, 0, v51
	v_sqrt_f32_e32 v51, v51
	v_rcp_f32_e32 v50, v50
	v_mul_f32_e32 v55, 0xbfb8aa3b, v55
	v_exp_f32_e32 v55, v55
	v_cndmask_b32_e64 v51, v51, 1.0, s[0:1]
	v_mul_f32_e32 v50, v50, v51
	v_mul_f32_e32 v56, v50, v94
	v_add_f32_e32 v50, 1.0, v55
	v_mul_f32_e32 v55, v68, v52
	v_add_f32_e32 v52, v53, v77
	v_mul_f32_e32 v52, 0xbfb8aa3b, v52
	v_exp_f32_e32 v52, v52
	v_add_f32_e32 v51, v55, v55
	v_mul_f32_e32 v51, 0x3fb8aa3b, v51
	v_add_f32_e32 v53, v57, v73
	v_add_f32_e32 v52, 1.0, v52
; __device__ __forceinline__ unsigned cvt_pk_bf16(float lo, float hi) { unsigned r; asm volatile("v_cvt_pk_bf16_f32 %0, %1, %2" : "=v"(r) : "v"(lo), "v"(hi)); return r; }
; __device__ __forceinline__ float bflo(unsigned w) { return __uint_as_float(w << 16); }
; __device__ __forceinline__ float bfhi(unsigned w) { return __uint_as_float(w & 0xffff0000u); }
; __device__ __forceinline__ float fast_sigmoid(float x) { return __builtin_amdgcn_rcpf(1.0f + __builtin_amdgcn_exp2f(-1.44269504089f * x)); }
; __device__ __forceinline__ float fast_exp(float x) { return __builtin_amdgcn_exp2f(1.44269504089f * x); }
;     __device__ __forceinline__ void operator()(const f32x4 (&acc)[2][2][4][2], const Unit& u, int wr, int wc, int fr, int fq, LAS unsigned char* lds) const {
;     ...
;             for (int m = 0; m < 4; ++m) { const int row = row0 + ai * HALF + m * 16; const size_t o = (size_t)row * D + c0;
;                 const bool first = d == 0 ? ((row & (LS - 1)) == 0 && row != LS) : ((row & (LS - 1)) == LS - 1 && row != LS - 1);
;                 const u32x4 xw = *(const u32x4*)(xb + o);
;                 const float xv[8] = {bflo(xw.x), bfhi(xw.x), bflo(xw.y), bfhi(xw.y), bflo(xw.z), bfhi(xw.z), bflo(xw.w), bfhi(xw.w)};
;                 float lo[8], bo[8];
; #pragma unroll
;                 for (int n = 0; n < 2; ++n)
; #pragma unroll
;                     for (int e = 0; e < 4; ++e) { const int qd = 4 * n + e; const float gx = fast_sigmoid(acc[ai][0][m][n][e] + vbx[n][e]), ga = fast_sigmoid(acc[ai][1][m][n][e] + vba[n][e]);
;                         const float l = ga * vls[n][e]; const float mult = first ? 1.0f : __builtin_amdgcn_sqrtf(fmaxf(1.0f - fast_exp(2.0f * l), 0.f)); lo[qd] = l; bo[qd] = mult * gx * xv[qd]; }
;                 u32x4 w; w.x = cvt_pk_bf16(lo[0], lo[1]); w.y = cvt_pk_bf16(lo[2], lo[3]); w.z = cvt_pk_bf16(lo[4], lo[5]); w.w = cvt_pk_bf16(lo[6], lo[7]); *(u32x4*)(LA + o) = w;
;                 w.x = cvt_pk_bf16(bo[0], bo[1]); w.y = cvt_pk_bf16(bo[2], bo[3]); w.z = cvt_pk_bf16(bo[4], bo[5]); w.w = cvt_pk_bf16(bo[6], bo[7]); *(u32x4*)(BB + o) = w; }
	v_rcp_f32_e32 v52, v52
	v_exp_f32_e32 v51, v51
	v_mul_f32_e32 v53, 0xbfb8aa3b, v53
	v_exp_f32_e32 v53, v53
	v_mul_f32_e32 v57, v69, v52
	v_add_f32_e32 v52, v57, v57
	v_mul_f32_e32 v52, 0x3fb8aa3b, v52
	v_exp_f32_e32 v52, v52
	v_sub_f32_e32 v51, 1.0, v51
	v_max_f32_e32 v51, 0, v51
	v_sqrt_f32_e32 v51, v51
	v_sub_f32_e32 v52, 1.0, v52
	v_rcp_f32_e32 v50, v50
	v_max_f32_e32 v52, 0, v52
	v_add_f32_e32 v53, 1.0, v53
	v_sqrt_f32_e32 v52, v52
	v_rcp_f32_e32 v53, v53
	v_cndmask_b32_e64 v51, v51, 1.0, s[0:1]
	v_mul_f32_e32 v50, v50, v51
	v_mul_f32_e32 v94, v50, v99
	v_cndmask_b32_e64 v50, v52, 1.0, s[0:1]
	v_mul_f32_e32 v50, v53, v50
	v_mul_f32_e32 v95, v50, v95
	v_cvt_pk_bf16_f32 v50, v58, v59
	v_cvt_pk_bf16_f32 v51, v60, v61
	v_cvt_pk_bf16_f32 v52, v92, v54
	v_cvt_pk_bf16_f32 v53, v55, v57
	v_lshl_add_u64 v[54:55], s[18:19], 0, v[90:91]
	global_store_dwordx4 v[54:55], v[50:53], off
	v_lshl_add_u64 v[54:55], s[16:17], 0, v[90:91]
	s_mov_b64 s[0:1], 0x48000
	v_cvt_pk_bf16_f32 v50, v62, v63
	v_cvt_pk_bf16_f32 v51, v64, v65
	v_cvt_pk_bf16_f32 v52, v93, v56
	v_cvt_pk_bf16_f32 v53, v94, v95
	global_store_dwordx4 v[54:55], v[50:53], off
	v_lshl_add_u64 v[54:55], v[162:163], 0, s[0:1]
	v_mul_f32_e32 v43, 0xbfb8aa3b, v43
	v_lshl_add_u64 v[50:51], s[20:21], 0, v[54:55]
	v_mov_b32_e32 v50, v204
	v_mov_b32_e32 v51, v205
	v_mov_b32_e32 v52, v206
	v_mov_b32_e32 v53, v207
	v_exp_f32_e32 v43, v43
	v_mul_f32_e32 v42, v82, v42
	v_add_f32_e32 v60, v42, v42
	v_add_f32_e32 v46, v46, v78
	v_add_f32_e32 v43, 1.0, v43
	v_mul_f32_e32 v60, 0x3fb8aa3b, v60
	v_rcp_f32_e32 v43, v43
	v_mul_f32_e32 v46, 0xbfb8aa3b, v46
	v_exp_f32_e32 v60, v60
	v_exp_f32_e32 v46, v46
	v_mul_f32_e32 v43, v83, v43
	v_add_f32_e32 v61, v43, v43
	v_sub_f32_e32 v60, 1.0, v60
	v_add_f32_e32 v45, v45, v89
	v_add_f32_e32 v46, 1.0, v46
	v_max_f32_e32 v60, 0, v60
	v_add_f32_e32 v47, v47, v79
	v_mul_f32_e32 v61, 0x3fb8aa3b, v61
	v_mul_f32_e32 v45, 0xbfb8aa3b, v45
	v_rcp_f32_e32 v46, v46
	v_sqrt_f32_e32 v60, v60
	v_mul_f32_e32 v47, 0xbfb8aa3b, v47
	v_exp_f32_e32 v61, v61
	v_exp_f32_e32 v45, v45
	v_exp_f32_e32 v47, v47
	v_mul_f32_e32 v46, v46, v60
	v_sub_f32_e32 v60, 1.0, v61
	v_add_f32_e32 v45, 1.0, v45
	v_add_f32_e32 v47, 1.0, v47
	v_max_f32_e32 v60, 0, v60
	v_rcp_f32_e32 v45, v45
	v_rcp_f32_e32 v47, v47
	v_sqrt_f32_e32 v60, v60
	v_add_f32_e32 v34, v34, v74
	v_mul_f32_e32 v34, 0xbfb8aa3b, v34
	v_mul_f32_e32 v45, v85, v45
	v_exp_f32_e32 v34, v34
	v_mul_f32_e32 v47, v47, v60
	v_add_f32_e32 v60, v45, v45
	v_add_f32_e32 v49, v49, v81
	v_mul_f32_e32 v60, 0x3fb8aa3b, v60
	v_mul_f32_e32 v49, 0xbfb8aa3b, v49
	v_exp_f32_e32 v60, v60
	v_add_f32_e32 v35, v35, v75
	v_exp_f32_e32 v49, v49
	v_add_f32_e32 v34, 1.0, v34
	v_mul_f32_e32 v35, 0xbfb8aa3b, v35
	v_rcp_f32_e32 v34, v34
	v_exp_f32_e32 v35, v35
	v_sub_f32_e32 v60, 1.0, v60
	v_add_f32_e32 v49, 1.0, v49
	v_max_f32_e32 v60, 0, v60
	v_rcp_f32_e32 v49, v49
	v_sqrt_f32_e32 v60, v60
	v_add_f32_e32 v35, 1.0, v35
	v_rcp_f32_e32 v35, v35
	v_add_f32_e32 v38, v38, v70
	v_mul_f32_e32 v38, 0xbfb8aa3b, v38
	v_mul_f32_e32 v49, v49, v60
	v_exp_f32_e32 v38, v38
	v_add_f32_e32 v39, v39, v71
	v_add_f32_e32 v36, v36, v76
	v_add_f32_e32 v44, v44, v88
	v_add_f32_e32 v38, 1.0, v38
	v_mul_f32_e32 v39, 0xbfb8aa3b, v39
	v_mul_f32_e32 v36, 0xbfb8aa3b, v36
	v_add_f32_e32 v37, v37, v77
	v_mul_f32_e32 v44, 0xbfb8aa3b, v44
	v_rcp_f32_e32 v38, v38
	v_exp_f32_e32 v39, v39
	v_exp_f32_e32 v36, v36
	v_mul_f32_e32 v37, 0xbfb8aa3b, v37
	v_exp_f32_e32 v44, v44
	v_exp_f32_e32 v37, v37
	v_add_f32_e32 v36, 1.0, v36
	v_rcp_f32_e32 v36, v36
	v_add_f32_e32 v44, 1.0, v44
	v_add_f32_e32 v37, 1.0, v37
	v_rcp_f32_e32 v44, v44
	s_nop 0
	v_lshlrev_b32_e32 v56, 16, v50
	v_and_b32_e32 v50, 0xffff0000, v50
	v_mul_f32_e32 v47, v47, v50
	v_mul_f32_e32 v50, v66, v34
	v_add_f32_e32 v34, v50, v50
	v_mul_f32_e32 v34, 0x3fb8aa3b, v34
	v_exp_f32_e32 v34, v34
	v_lshlrev_b32_e32 v57, 16, v51
	v_and_b32_e32 v51, 0xffff0000, v51
	v_mul_f32_e32 v49, v49, v51
	v_mul_f32_e32 v51, v67, v35
	v_add_f32_e32 v35, v51, v51
	v_sub_f32_e32 v34, 1.0, v34
	v_mul_f32_e32 v35, 0x3fb8aa3b, v35
	v_max_f32_e32 v34, 0, v34
	v_exp_f32_e32 v35, v35
	v_sqrt_f32_e32 v34, v34
	v_rcp_f32_e32 v37, v37
	v_lshlrev_b32_e32 v58, 16, v52
	v_sub_f32_e32 v35, 1.0, v35
	v_mul_f32_e32 v34, v38, v34
	v_add_f32_e32 v38, 1.0, v39
	v_max_f32_e32 v35, 0, v35
	v_rcp_f32_e32 v38, v38
	v_sqrt_f32_e32 v35, v35
	v_add_f32_e32 v39, v40, v72
	v_mul_f32_e32 v39, 0xbfb8aa3b, v39
	v_exp_f32_e32 v39, v39
	v_mul_f32_e32 v40, v34, v58
	v_mul_f32_e32 v34, v38, v35
	v_mul_f32_e32 v38, v68, v36
	v_mul_f32_e32 v44, v84, v44
	v_add_f32_e32 v36, v38, v38
	v_mul_f32_e32 v37, v69, v37
	v_mul_f32_e32 v46, v46, v56
	v_add_f32_e32 v56, v44, v44
	v_add_f32_e32 v35, 1.0, v39
	v_mul_f32_e32 v36, 0x3fb8aa3b, v36
	v_add_f32_e32 v39, v41, v73
	v_add_f32_e32 v41, v37, v37
	v_add_f32_e32 v48, v48, v80
	v_mul_f32_e32 v56, 0x3fb8aa3b, v56
	v_exp_f32_e32 v36, v36
	v_mul_f32_e32 v41, 0x3fb8aa3b, v41
	v_mul_f32_e32 v48, 0xbfb8aa3b, v48
	v_exp_f32_e32 v56, v56
	v_mul_f32_e32 v39, 0xbfb8aa3b, v39
	v_exp_f32_e32 v41, v41
	v_exp_f32_e32 v48, v48
	v_exp_f32_e32 v39, v39
	v_sub_f32_e32 v36, 1.0, v36
	v_sub_f32_e32 v56, 1.0, v56
	v_max_f32_e32 v36, 0, v36
	v_sub_f32_e32 v41, 1.0, v41
	v_add_f32_e32 v48, 1.0, v48
	v_max_f32_e32 v56, 0, v56
	v_rcp_f32_e32 v35, v35
	v_sqrt_f32_e32 v36, v36
	v_add_f32_e32 v39, 1.0, v39
	v_max_f32_e32 v41, 0, v41
	v_rcp_f32_e32 v48, v48
	v_sqrt_f32_e32 v56, v56
	v_rcp_f32_e32 v39, v39
	v_sqrt_f32_e32 v41, v41
	v_and_b32_e32 v52, 0xffff0000, v52
	v_lshlrev_b32_e32 v59, 16, v53
	v_mul_f32_e32 v52, v34, v52
	v_mul_f32_e32 v34, v35, v36
	v_and_b32_e32 v53, 0xffff0000, v53
; __device__ __forceinline__ unsigned cvt_pk_bf16(float lo, float hi) { unsigned r; asm volatile("v_cvt_pk_bf16_f32 %0, %1, %2" : "=v"(r) : "v"(lo), "v"(hi)); return r; }
; __device__ __forceinline__ float bflo(unsigned w) { return __uint_as_float(w << 16); }
; __device__ __forceinline__ float bfhi(unsigned w) { return __uint_as_float(w & 0xffff0000u); }
; __device__ __forceinline__ float fast_sigmoid(float x) { return __builtin_amdgcn_rcpf(1.0f + __builtin_amdgcn_exp2f(-1.44269504089f * x)); }
; __device__ __forceinline__ float fast_exp(float x) { return __builtin_amdgcn_exp2f(1.44269504089f * x); }
;     __device__ __forceinline__ void operator()(const f32x4 (&acc)[2][2][4][2], const Unit& u, int wr, int wc, int fr, int fq, LAS unsigned char* lds) const {
;     ...
;             for (int m = 0; m < 4; ++m) { const int row = row0 + ai * HALF + m * 16; const size_t o = (size_t)row * D + c0;
;                 const bool first = d == 0 ? ((row & (LS - 1)) == 0 && row != LS) : ((row & (LS - 1)) == LS - 1 && row != LS - 1);
;                 const u32x4 xw = *(const u32x4*)(xb + o);
;                 const float xv[8] = {bflo(xw.x), bfhi(xw.x), bflo(xw.y), bfhi(xw.y), bflo(xw.z), bfhi(xw.z), bflo(xw.w), bfhi(xw.w)};
;                 float lo[8], bo[8];
; #pragma unroll
;                 for (int n = 0; n < 2; ++n)
; #pragma unroll
;                     for (int e = 0; e < 4; ++e) { const int qd = 4 * n + e; const float gx = fast_sigmoid(acc[ai][0][m][n][e] + vbx[n][e]), ga = fast_sigmoid(acc[ai][1][m][n][e] + vba[n][e]);
;                         const float l = ga * vls[n][e]; const float mult = first ? 1.0f : __builtin_amdgcn_sqrtf(fmaxf(1.0f - fast_exp(2.0f * l), 0.f)); lo[qd] = l; bo[qd] = mult * gx * xv[qd]; }
;                 u32x4 w; w.x = cvt_pk_bf16(lo[0], lo[1]); w.y = cvt_pk_bf16(lo[2], lo[3]); w.z = cvt_pk_bf16(lo[4], lo[5]); w.w = cvt_pk_bf16(lo[6], lo[7]); *(u32x4*)(LA + o) = w;
;                 w.x = cvt_pk_bf16(bo[0], bo[1]); w.y = cvt_pk_bf16(bo[2], bo[3]); w.z = cvt_pk_bf16(bo[4], bo[5]); w.w = cvt_pk_bf16(bo[6], bo[7]); *(u32x4*)(BB + o) = w; }
	v_mul_f32_e32 v48, v48, v56
	v_mul_f32_e32 v56, v34, v59
	v_mul_f32_e32 v34, v39, v41
	v_mul_f32_e32 v41, v34, v53
	v_cvt_pk_bf16_f32 v34, v42, v43
	v_cvt_pk_bf16_f32 v35, v44, v45
	v_cvt_pk_bf16_f32 v36, v50, v51
	v_cvt_pk_bf16_f32 v37, v38, v37
	v_lshl_add_u64 v[38:39], s[18:19], 0, v[54:55]
	global_store_dwordx4 v[38:39], v[34:37], off
	v_lshl_add_u64 v[38:39], s[16:17], 0, v[54:55]
	s_mov_b64 s[0:1], 0x50000
	v_mul_f32_e32 v48, v48, v57
	v_cvt_pk_bf16_f32 v34, v46, v47
	v_cvt_pk_bf16_f32 v35, v48, v49
	v_cvt_pk_bf16_f32 v36, v40, v52
	v_cvt_pk_bf16_f32 v37, v56, v41
	global_store_dwordx4 v[38:39], v[34:37], off
	v_lshl_add_u64 v[38:39], v[162:163], 0, s[0:1]
	v_add_f32_e32 v26, v26, v86
	v_lshl_add_u64 v[34:35], s[20:21], 0, v[38:39]
	v_mov_b32_e32 v34, v208
	v_mov_b32_e32 v35, v209
	v_mov_b32_e32 v36, v210
	v_mov_b32_e32 v37, v211
	v_mul_f32_e32 v26, 0xbfb8aa3b, v26
	v_exp_f32_e32 v26, v26
	v_add_f32_e32 v27, v27, v87
	v_mul_f32_e32 v27, 0xbfb8aa3b, v27
	v_exp_f32_e32 v27, v27
	v_add_f32_e32 v26, 1.0, v26
	v_rcp_f32_e32 v26, v26
	v_add_f32_e32 v30, v30, v78
	v_add_f32_e32 v27, 1.0, v27
	v_rcp_f32_e32 v27, v27
	v_mul_f32_e32 v26, v82, v26
	v_add_f32_e32 v44, v26, v26
	v_mul_f32_e32 v44, 0x3fb8aa3b, v44
	v_mul_f32_e32 v30, 0xbfb8aa3b, v30
	v_exp_f32_e32 v44, v44
	v_exp_f32_e32 v30, v30
	v_mul_f32_e32 v27, v83, v27
	v_add_f32_e32 v45, v27, v27
	v_sub_f32_e32 v44, 1.0, v44
	v_add_f32_e32 v29, v29, v89
	v_add_f32_e32 v30, 1.0, v30
	v_max_f32_e32 v44, 0, v44
	v_add_f32_e32 v31, v31, v79
	v_mul_f32_e32 v45, 0x3fb8aa3b, v45
	v_mul_f32_e32 v29, 0xbfb8aa3b, v29
	v_rcp_f32_e32 v30, v30
	v_sqrt_f32_e32 v44, v44
	v_mul_f32_e32 v31, 0xbfb8aa3b, v31
	v_exp_f32_e32 v45, v45
	v_exp_f32_e32 v29, v29
	v_exp_f32_e32 v31, v31
	v_mul_f32_e32 v30, v30, v44
	v_sub_f32_e32 v44, 1.0, v45
	v_add_f32_e32 v29, 1.0, v29
	v_add_f32_e32 v31, 1.0, v31
	v_max_f32_e32 v44, 0, v44
	v_rcp_f32_e32 v29, v29
	v_rcp_f32_e32 v31, v31
	v_sqrt_f32_e32 v44, v44
	v_add_f32_e32 v18, v18, v74
	v_mul_f32_e32 v18, 0xbfb8aa3b, v18
	v_mul_f32_e32 v29, v85, v29
	v_exp_f32_e32 v18, v18
	v_mul_f32_e32 v31, v31, v44
	v_add_f32_e32 v44, v29, v29
	v_add_f32_e32 v33, v33, v81
	v_mul_f32_e32 v44, 0x3fb8aa3b, v44
	v_mul_f32_e32 v33, 0xbfb8aa3b, v33
	v_exp_f32_e32 v44, v44
	v_add_f32_e32 v19, v19, v75
	v_exp_f32_e32 v33, v33
	v_add_f32_e32 v18, 1.0, v18
	v_mul_f32_e32 v19, 0xbfb8aa3b, v19
	v_rcp_f32_e32 v18, v18
	v_exp_f32_e32 v19, v19
	v_sub_f32_e32 v44, 1.0, v44
	v_add_f32_e32 v33, 1.0, v33
	v_max_f32_e32 v44, 0, v44
	v_rcp_f32_e32 v33, v33
	v_sqrt_f32_e32 v44, v44
	v_add_f32_e32 v19, 1.0, v19
	v_rcp_f32_e32 v19, v19
	v_add_f32_e32 v22, v22, v70
	v_mul_f32_e32 v22, 0xbfb8aa3b, v22
	v_mul_f32_e32 v33, v33, v44
	v_exp_f32_e32 v22, v22
	v_add_f32_e32 v23, v23, v71
	v_add_f32_e32 v20, v20, v76
	v_add_f32_e32 v28, v28, v88
	v_add_f32_e32 v22, 1.0, v22
	v_mul_f32_e32 v23, 0xbfb8aa3b, v23
	v_mul_f32_e32 v20, 0xbfb8aa3b, v20
	v_add_f32_e32 v21, v21, v77
	v_mul_f32_e32 v28, 0xbfb8aa3b, v28
	v_rcp_f32_e32 v22, v22
	v_exp_f32_e32 v23, v23
	v_exp_f32_e32 v20, v20
	v_mul_f32_e32 v21, 0xbfb8aa3b, v21
	v_exp_f32_e32 v28, v28
	s_nop 0
	v_lshlrev_b32_e32 v40, 16, v34
	v_and_b32_e32 v34, 0xffff0000, v34
	v_mul_f32_e32 v31, v31, v34
	v_mul_f32_e32 v34, v66, v18
	v_add_f32_e32 v18, v34, v34
	v_mul_f32_e32 v18, 0x3fb8aa3b, v18
	v_exp_f32_e32 v18, v18
	v_lshlrev_b32_e32 v41, 16, v35
	v_and_b32_e32 v35, 0xffff0000, v35
	v_mul_f32_e32 v33, v33, v35
	v_mul_f32_e32 v35, v67, v19
	v_add_f32_e32 v19, v35, v35
	v_sub_f32_e32 v18, 1.0, v18
	v_mul_f32_e32 v19, 0x3fb8aa3b, v19
	v_max_f32_e32 v18, 0, v18
	v_exp_f32_e32 v19, v19
	v_sqrt_f32_e32 v18, v18
	v_exp_f32_e32 v21, v21
	v_add_f32_e32 v20, 1.0, v20
	v_sub_f32_e32 v19, 1.0, v19
	v_mul_f32_e32 v18, v22, v18
	v_add_f32_e32 v22, 1.0, v23
	v_max_f32_e32 v19, 0, v19
	v_add_f32_e32 v28, 1.0, v28
	v_rcp_f32_e32 v22, v22
	v_sqrt_f32_e32 v19, v19
	v_add_f32_e32 v23, v24, v72
	v_rcp_f32_e32 v20, v20
	v_add_f32_e32 v21, 1.0, v21
	v_rcp_f32_e32 v28, v28
	v_mul_f32_e32 v23, 0xbfb8aa3b, v23
	v_rcp_f32_e32 v21, v21
	v_exp_f32_e32 v23, v23
	v_lshlrev_b32_e32 v42, 16, v36
	v_mul_f32_e32 v24, v18, v42
	v_mul_f32_e32 v18, v22, v19
	v_mul_f32_e32 v22, v68, v20
	v_mul_f32_e32 v28, v84, v28
	v_add_f32_e32 v20, v22, v22
	v_mul_f32_e32 v21, v69, v21
	v_mul_f32_e32 v30, v30, v40
	v_add_f32_e32 v40, v28, v28
	v_add_f32_e32 v19, 1.0, v23
	v_mul_f32_e32 v20, 0x3fb8aa3b, v20
	v_add_f32_e32 v23, v25, v73
	v_add_f32_e32 v25, v21, v21
	v_add_f32_e32 v32, v32, v80
	v_mul_f32_e32 v40, 0x3fb8aa3b, v40
	v_exp_f32_e32 v20, v20
	v_mul_f32_e32 v25, 0x3fb8aa3b, v25
	v_mul_f32_e32 v32, 0xbfb8aa3b, v32
	v_exp_f32_e32 v40, v40
	v_mul_f32_e32 v23, 0xbfb8aa3b, v23
	v_exp_f32_e32 v25, v25
	v_exp_f32_e32 v32, v32
	v_exp_f32_e32 v23, v23
	v_sub_f32_e32 v20, 1.0, v20
	v_sub_f32_e32 v40, 1.0, v40
	v_max_f32_e32 v20, 0, v20
	v_sub_f32_e32 v25, 1.0, v25
	v_add_f32_e32 v32, 1.0, v32
	v_max_f32_e32 v40, 0, v40
	v_rcp_f32_e32 v19, v19
	v_sqrt_f32_e32 v20, v20
	v_add_f32_e32 v23, 1.0, v23
	v_max_f32_e32 v25, 0, v25
	v_rcp_f32_e32 v32, v32
	v_sqrt_f32_e32 v40, v40
	v_rcp_f32_e32 v23, v23
	v_sqrt_f32_e32 v25, v25
	v_and_b32_e32 v36, 0xffff0000, v36
	v_lshlrev_b32_e32 v43, 16, v37
	v_mul_f32_e32 v36, v18, v36
	v_mul_f32_e32 v18, v19, v20
	v_and_b32_e32 v37, 0xffff0000, v37
	v_mul_f32_e32 v32, v32, v40
	v_mul_f32_e32 v40, v18, v43
	v_mul_f32_e32 v18, v23, v25
	v_mul_f32_e32 v25, v18, v37
	v_cvt_pk_bf16_f32 v18, v26, v27
	v_cvt_pk_bf16_f32 v19, v28, v29
	v_cvt_pk_bf16_f32 v20, v34, v35
	v_cvt_pk_bf16_f32 v21, v22, v21
	v_lshl_add_u64 v[22:23], s[18:19], 0, v[38:39]
	v_mul_f32_e32 v32, v32, v41
	global_store_dwordx4 v[22:23], v[18:21], off
; __device__ __forceinline__ unsigned cvt_pk_bf16(float lo, float hi) { unsigned r; asm volatile("v_cvt_pk_bf16_f32 %0, %1, %2" : "=v"(r) : "v"(lo), "v"(hi)); return r; }
; __device__ __forceinline__ float bflo(unsigned w) { return __uint_as_float(w << 16); }
; __device__ __forceinline__ float bfhi(unsigned w) { return __uint_as_float(w & 0xffff0000u); }
; __device__ __forceinline__ float fast_sigmoid(float x) { return __builtin_amdgcn_rcpf(1.0f + __builtin_amdgcn_exp2f(-1.44269504089f * x)); }
; __device__ __forceinline__ float fast_exp(float x) { return __builtin_amdgcn_exp2f(1.44269504089f * x); }
;     __device__ __forceinline__ void operator()(const f32x4 (&acc)[2][2][4][2], const Unit& u, int wr, int wc, int fr, int fq, LAS unsigned char* lds) const {
;     ...
;             for (int m = 0; m < 4; ++m) { const int row = row0 + ai * HALF + m * 16; const size_t o = (size_t)row * D + c0;
;                 const bool first = d == 0 ? ((row & (LS - 1)) == 0 && row != LS) : ((row & (LS - 1)) == LS - 1 && row != LS - 1);
;                 const u32x4 xw = *(const u32x4*)(xb + o);
;                 const float xv[8] = {bflo(xw.x), bfhi(xw.x), bflo(xw.y), bfhi(xw.y), bflo(xw.z), bfhi(xw.z), bflo(xw.w), bfhi(xw.w)};
;                 float lo[8], bo[8];
; #pragma unroll
;                 for (int n = 0; n < 2; ++n)
; #pragma unroll
;                     for (int e = 0; e < 4; ++e) { const int qd = 4 * n + e; const float gx = fast_sigmoid(acc[ai][0][m][n][e] + vbx[n][e]), ga = fast_sigmoid(acc[ai][1][m][n][e] + vba[n][e]);
;                         const float l = ga * vls[n][e]; const float mult = first ? 1.0f : __builtin_amdgcn_sqrtf(fmaxf(1.0f - fast_exp(2.0f * l), 0.f)); lo[qd] = l; bo[qd] = mult * gx * xv[qd]; }
;                 u32x4 w; w.x = cvt_pk_bf16(lo[0], lo[1]); w.y = cvt_pk_bf16(lo[2], lo[3]); w.z = cvt_pk_bf16(lo[4], lo[5]); w.w = cvt_pk_bf16(lo[6], lo[7]); *(u32x4*)(LA + o) = w;
;                 w.x = cvt_pk_bf16(bo[0], bo[1]); w.y = cvt_pk_bf16(bo[2], bo[3]); w.z = cvt_pk_bf16(bo[4], bo[5]); w.w = cvt_pk_bf16(bo[6], bo[7]); *(u32x4*)(BB + o) = w; }
	v_lshl_add_u64 v[22:23], s[16:17], 0, v[38:39]
	v_add_f32_e32 v10, v10, v86
	v_cvt_pk_bf16_f32 v18, v30, v31
	v_cvt_pk_bf16_f32 v19, v32, v33
	v_cvt_pk_bf16_f32 v20, v24, v36
	v_add_u32_e32 v24, 0xb0, v160
	v_cvt_pk_bf16_f32 v21, v40, v25
	v_ashrrev_i32_e32 v25, 31, v24
	global_store_dwordx4 v[22:23], v[18:21], off
	v_mul_f32_e32 v10, 0xbfb8aa3b, v10
	v_exp_f32_e32 v10, v10
	v_lshlrev_b64 v[18:19], 11, v[24:25]
	v_or_b32_e32 v18, v18, v161
	v_lshl_add_u64 v[20:21], s[20:21], 0, v[18:19]
	v_mov_b32_e32 v20, v212
	v_mov_b32_e32 v21, v213
	v_mov_b32_e32 v22, v214
	v_mov_b32_e32 v23, v215
	v_add_f32_e32 v10, 1.0, v10
	v_rcp_f32_e32 v10, v10
	v_add_f32_e32 v11, v11, v87
	v_add_f32_e32 v14, v14, v78
	v_mul_f32_e32 v11, 0xbfb8aa3b, v11
	v_mul_f32_e32 v10, v82, v10
	v_add_f32_e32 v28, v10, v10
	v_mul_f32_e32 v28, 0x3fb8aa3b, v28
	v_exp_f32_e32 v28, v28
	v_mul_f32_e32 v14, 0xbfb8aa3b, v14
	v_exp_f32_e32 v11, v11
	v_exp_f32_e32 v14, v14
	v_sub_f32_e32 v28, 1.0, v28
	v_max_f32_e32 v28, 0, v28
	v_add_f32_e32 v11, 1.0, v11
	v_and_b32_e32 v25, 0x1fff, v24
	v_add_f32_e32 v14, 1.0, v14
	v_sqrt_f32_e32 v28, v28
	v_rcp_f32_e32 v11, v11
	v_cmp_ne_u32_e32 vcc, s9, v25
	v_cmp_eq_u32_e64 s[0:1], s9, v24
	v_rcp_f32_e32 v14, v14
	s_or_b64 s[0:1], s[0:1], vcc
	s_or_b64 vcc, s[22:23], s[0:1]
	v_cndmask_b32_e32 v28, 1.0, v28, vcc
	v_mul_f32_e32 v11, v83, v11
	v_mul_f32_e32 v14, v14, v28
	v_add_f32_e32 v28, v11, v11
	v_mul_f32_e32 v28, 0x3fb8aa3b, v28
	v_add_f32_e32 v12, v12, v88
	v_exp_f32_e32 v28, v28
	v_add_f32_e32 v15, v15, v79
	v_mul_f32_e32 v12, 0xbfb8aa3b, v12
	v_mul_f32_e32 v15, 0xbfb8aa3b, v15
	v_exp_f32_e32 v12, v12
	v_exp_f32_e32 v15, v15
	v_sub_f32_e32 v28, 1.0, v28
	v_max_f32_e32 v28, 0, v28
	v_add_f32_e32 v12, 1.0, v12
	v_sqrt_f32_e32 v28, v28
	v_add_f32_e32 v15, 1.0, v15
	v_rcp_f32_e32 v12, v12
	v_rcp_f32_e32 v15, v15
	v_add_f32_e32 v13, v13, v89
	v_add_f32_e32 v16, v16, v80
	v_mul_f32_e32 v12, v84, v12
	v_mul_f32_e32 v13, 0xbfb8aa3b, v13
	v_mul_f32_e32 v16, 0xbfb8aa3b, v16
	v_exp_f32_e32 v13, v13
	v_exp_f32_e32 v16, v16
	v_add_f32_e32 v17, v17, v81
	v_add_f32_e32 v0, v0, v74
	v_add_f32_e32 v13, 1.0, v13
	v_add_f32_e32 v16, 1.0, v16
	v_rcp_f32_e32 v13, v13
	v_rcp_f32_e32 v16, v16
	v_mul_f32_e32 v17, 0xbfb8aa3b, v17
	v_mul_f32_e32 v0, 0xbfb8aa3b, v0
	v_mul_f32_e32 v13, v85, v13
	v_exp_f32_e32 v17, v17
	v_exp_f32_e32 v0, v0
	v_add_f32_e32 v6, v6, v70
	v_add_f32_e32 v1, v1, v75
	v_add_f32_e32 v17, 1.0, v17
	v_add_f32_e32 v0, 1.0, v0
	v_rcp_f32_e32 v17, v17
	v_rcp_f32_e32 v0, v0
	v_mul_f32_e32 v6, 0xbfb8aa3b, v6
	v_mul_f32_e32 v1, 0xbfb8aa3b, v1
	v_exp_f32_e32 v6, v6
	v_exp_f32_e32 v1, v1
	v_add_f32_e32 v7, v7, v71
	v_mul_f32_e32 v7, 0xbfb8aa3b, v7
	v_add_f32_e32 v6, 1.0, v6
	v_add_f32_e32 v1, 1.0, v1
	v_rcp_f32_e32 v6, v6
	v_rcp_f32_e32 v1, v1
	v_add_f32_e32 v2, v2, v76
	v_exp_f32_e32 v7, v7
	s_nop 0
	v_lshlrev_b32_e32 v24, 16, v20
	v_mul_f32_e32 v14, v14, v24
	v_cndmask_b32_e32 v24, 1.0, v28, vcc
	v_mul_f32_e32 v15, v15, v24
	v_add_f32_e32 v24, v12, v12
	v_mul_f32_e32 v24, 0x3fb8aa3b, v24
	v_exp_f32_e32 v24, v24
	v_and_b32_e32 v20, 0xffff0000, v20
	v_mul_f32_e32 v15, v15, v20
	v_mul_f32_e32 v2, 0xbfb8aa3b, v2
	v_sub_f32_e32 v24, 1.0, v24
	v_max_f32_e32 v24, 0, v24
	v_sqrt_f32_e32 v24, v24
	v_exp_f32_e32 v2, v2
	v_lshlrev_b32_e32 v25, 16, v21
	v_and_b32_e32 v21, 0xffff0000, v21
	v_cndmask_b32_e32 v20, 1.0, v24, vcc
	v_mul_f32_e32 v16, v16, v20
	v_add_f32_e32 v20, v13, v13
	v_mul_f32_e32 v20, 0x3fb8aa3b, v20
	v_exp_f32_e32 v20, v20
	v_lshlrev_b32_e32 v26, 16, v22
	v_add_f32_e32 v2, 1.0, v2
	v_rcp_f32_e32 v2, v2
	v_sub_f32_e32 v20, 1.0, v20
	v_max_f32_e32 v20, 0, v20
	v_sqrt_f32_e32 v20, v20
	v_and_b32_e32 v22, 0xffff0000, v22
	v_lshlrev_b32_e32 v27, 16, v23
	v_and_b32_e32 v23, 0xffff0000, v23
	v_cndmask_b32_e32 v20, 1.0, v20, vcc
	v_mul_f32_e32 v17, v17, v20
	v_mul_f32_e32 v20, v66, v0
	v_add_f32_e32 v0, v20, v20
	v_mul_f32_e32 v0, 0x3fb8aa3b, v0
	v_exp_f32_e32 v0, v0
	v_mul_f32_e32 v17, v17, v21
	s_mov_b32 s0, s6
	v_mul_f32_e32 v16, v16, v25
	v_sub_f32_e32 v0, 1.0, v0
	v_max_f32_e32 v0, 0, v0
	v_sqrt_f32_e32 v0, v0
	s_nop 0
	v_cndmask_b32_e32 v0, 1.0, v0, vcc
	v_mul_f32_e32 v0, v6, v0
	v_mul_f32_e32 v6, v67, v1
	v_add_f32_e32 v1, v6, v6
	v_mul_f32_e32 v1, 0x3fb8aa3b, v1
	v_exp_f32_e32 v1, v1
	v_mul_f32_e32 v21, v0, v26
	v_add_f32_e32 v0, 1.0, v7
	v_add_f32_e32 v7, v8, v72
	v_sub_f32_e32 v1, 1.0, v1
	v_max_f32_e32 v1, 0, v1
	v_sqrt_f32_e32 v1, v1
	v_rcp_f32_e32 v0, v0
	v_mul_f32_e32 v7, 0xbfb8aa3b, v7
	v_exp_f32_e32 v7, v7
	v_cndmask_b32_e32 v1, 1.0, v1, vcc
	v_mul_f32_e32 v0, v0, v1
	v_mul_f32_e32 v8, v0, v22
	v_add_f32_e32 v0, 1.0, v7
	v_mul_f32_e32 v7, v68, v2
	v_add_f32_e32 v2, v3, v77
	v_mul_f32_e32 v2, 0xbfb8aa3b, v2
	v_exp_f32_e32 v2, v2
	v_add_f32_e32 v1, v7, v7
	v_mul_f32_e32 v1, 0x3fb8aa3b, v1
	v_add_f32_e32 v3, v9, v73
	v_add_f32_e32 v2, 1.0, v2
	v_rcp_f32_e32 v2, v2
	v_exp_f32_e32 v1, v1
	v_mul_f32_e32 v3, 0xbfb8aa3b, v3
	v_exp_f32_e32 v3, v3
	v_mul_f32_e32 v9, v69, v2
	v_add_f32_e32 v2, v9, v9
	v_mul_f32_e32 v2, 0x3fb8aa3b, v2
	v_exp_f32_e32 v2, v2
	v_sub_f32_e32 v1, 1.0, v1
	v_max_f32_e32 v1, 0, v1
	v_sqrt_f32_e32 v1, v1
	v_sub_f32_e32 v2, 1.0, v2
	v_rcp_f32_e32 v0, v0
	v_max_f32_e32 v2, 0, v2
	v_add_f32_e32 v3, 1.0, v3
	v_sqrt_f32_e32 v2, v2
	v_rcp_f32_e32 v3, v3
	v_cndmask_b32_e32 v1, 1.0, v1, vcc
	v_mul_f32_e32 v0, v0, v1
	v_mul_f32_e32 v22, v0, v27
	v_cndmask_b32_e32 v0, 1.0, v2, vcc
	v_mul_f32_e32 v0, v3, v0
	v_mul_f32_e32 v23, v0, v23
	v_cvt_pk_bf16_f32 v0, v10, v11
	v_cvt_pk_bf16_f32 v1, v12, v13
	v_cvt_pk_bf16_f32 v2, v20, v6
	v_cvt_pk_bf16_f32 v3, v7, v9
	v_lshl_add_u64 v[6:7], s[18:19], 0, v[18:19]
	global_store_dwordx4 v[6:7], v[0:3], off
	v_lshl_add_u64 v[6:7], s[16:17], 0, v[18:19]
	s_and_b64 vcc, exec, s[10:11]
	s_mov_b64 s[16:17], s[14:15]
	s_mov_b64 s[18:19], s[12:13]
	v_cvt_pk_bf16_f32 v0, v14, v15
	v_cvt_pk_bf16_f32 v1, v16, v17
	v_cvt_pk_bf16_f32 v2, v21, v8
	v_cvt_pk_bf16_f32 v3, v22, v23
	global_store_dwordx4 v[6:7], v[0:3], off
	s_cbranch_vccz .LBB1_278
	s_waitcnt vmcnt(0)
	s_cmpk_gt_u32 s38, 0xff
	v_readlane_b32 s68, v254, 38
	s_movk_i32 s71, 0x1ff
	s_movk_i32 s72, 0x1800
	s_mov_b32 s83, s67
	s_mov_b32 s61, s74
	s_cbranch_scc1 .LBB1_285
	s_barrier
